# MO8+TRIM + Z0: accumulator zeroing removed, first K-iteration's first MFMA per accumulator takes srcC=0 (branch-selected segment copy)
# baseline (speedup 1.0000x reference)
.LBB0_138:
	s_ashr_i32 s9, s8, 31
	s_lshl_b64 s[14:15], s[8:9], 21
	s_add_u32 s14, s88, s14
	s_addc_u32 s15, s89, s15
	s_and_b64 s[16:17], s[0:1], exec
	s_cselect_b32 s9, s15, s19
	s_cselect_b32 s44, s14, s18
	s_ashr_i32 s7, s6, 31
	s_lshl_b64 s[16:17], s[6:7], 21
	v_readlane_b32 s7, v255, 31
	s_add_u32 s16, s7, s16
	v_readlane_b32 s7, v255, 32
	s_addc_u32 s17, s7, s17
	s_and_b64 s[24:25], s[0:1], exec
	s_cselect_b32 s7, s17, s23
	s_cselect_b32 s45, s16, s22
	s_add_u32 s18, s18, 0x100080
	s_addc_u32 s19, s19, 0
	s_add_u32 s46, s22, 0x100
	s_addc_u32 s47, s23, 0
	s_mov_b32 s48, -2
.LBB0_139:
	s_add_u32 s22, s18, 0xfff00080
	s_addc_u32 s23, s19, -1
	s_add_i32 s49, 0, 0x10000
	s_cmp_eq_u32 s48, 60
	s_cselect_b32 s25, s9, s23
	s_cselect_b32 s24, s44, s22
	s_cselect_b32 s23, s7, s47
	s_cselect_b32 s22, s45, s46
	s_add_i32 s52, 0, 0x14000
	v_add_u32_e32 v156, s49, v145
	v_add_u32_e32 v172, s52, v145
	ds_read_b128 v[140:143], v156
	ds_read_b128 v[148:151], v156 offset:1024
	ds_read_b128 v[152:155], v156 offset:2048
	ds_read_b128 v[156:159], v156 offset:3072
	ds_read_b128 v[160:163], v172
	ds_read_b128 v[164:167], v172 offset:1024
	ds_read_b128 v[168:171], v172 offset:2048
	ds_read_b128 v[190:193], v172 offset:3072
	v_lshl_add_u64 v[172:173], s[18:19], 0, v[136:137]
	s_add_i32 m0, s31, 0xc000
	ds_read_b128 v[194:197], v147
	ds_read_b128 v[198:201], v147 offset:1024
	ds_read_b128 v[202:205], v147 offset:2048
	ds_read_b128 v[206:209], v147 offset:3072
	ds_read_b128 v[228:231], v147 offset:4096
	ds_read_b128 v[232:235], v147 offset:5120
	ds_read_b128 v[236:239], v147 offset:6144
	ds_read_b128 v[240:243], v147 offset:7168
	global_load_lds_dwordx4 v[172:173], off
	v_lshl_add_u64 v[172:173], s[18:19], 0, v[138:139]
	s_add_i32 m0, s31, 0xe000
	s_nop 0
	global_load_lds_dwordx4 v[172:173], off
	s_waitcnt vmcnt(8)
	s_waitcnt lgkmcnt(0)
	s_cmp_eq_u32 s48, -2
	s_cbranch_scc1 .Lz0_0_0
	s_setprio 1
	s_barrier
	v_mfma_f32_16x16x32_bf16 v[126:129], v[140:143], v[194:197], v[126:129]
	v_mfma_f32_16x16x32_bf16 v[126:129], v[148:151], v[198:201], v[126:129]
	v_mfma_f32_16x16x32_bf16 v[118:121], v[148:151], v[206:209], v[118:121]
	v_mfma_f32_16x16x32_bf16 v[118:121], v[140:143], v[202:205], v[118:121]
	v_mfma_f32_16x16x32_bf16 v[102:105], v[140:143], v[228:231], v[102:105]
	v_mfma_f32_16x16x32_bf16 v[102:105], v[148:151], v[232:235], v[102:105]
	v_mfma_f32_16x16x32_bf16 v[86:89], v[148:151], v[240:243], v[86:89]
	v_mfma_f32_16x16x32_bf16 v[86:89], v[140:143], v[236:239], v[86:89]
	v_mfma_f32_16x16x32_bf16 v[78:81], v[152:155], v[236:239], v[78:81]
	v_mfma_f32_16x16x32_bf16 v[78:81], v[156:159], v[240:243], v[78:81]
	v_mfma_f32_16x16x32_bf16 v[94:97], v[156:159], v[232:235], v[94:97]
	v_mfma_f32_16x16x32_bf16 v[94:97], v[152:155], v[228:231], v[94:97]
	v_mfma_f32_16x16x32_bf16 v[110:113], v[152:155], v[202:205], v[110:113]
	v_mfma_f32_16x16x32_bf16 v[110:113], v[156:159], v[206:209], v[110:113]
	v_mfma_f32_16x16x32_bf16 v[122:125], v[156:159], v[198:201], v[122:125]
	v_mfma_f32_16x16x32_bf16 v[122:125], v[152:155], v[194:197], v[122:125]
	v_mfma_f32_16x16x32_bf16 v[114:117], v[160:163], v[194:197], v[114:117]
	v_mfma_f32_16x16x32_bf16 v[114:117], v[164:167], v[198:201], v[114:117]
	v_mfma_f32_16x16x32_bf16 v[98:101], v[164:167], v[206:209], v[98:101]
	v_mfma_f32_16x16x32_bf16 v[98:101], v[160:163], v[202:205], v[98:101]
	v_mfma_f32_16x16x32_bf16 v[82:85], v[160:163], v[228:231], v[82:85]
	v_mfma_f32_16x16x32_bf16 v[82:85], v[164:167], v[232:235], v[82:85]
	v_mfma_f32_16x16x32_bf16 v[70:73], v[164:167], v[240:243], v[70:73]
	v_mfma_f32_16x16x32_bf16 v[70:73], v[160:163], v[236:239], v[70:73]
	v_mfma_f32_16x16x32_bf16 v[66:69], v[168:171], v[236:239], v[66:69]
	v_mfma_f32_16x16x32_bf16 v[66:69], v[190:193], v[240:243], v[66:69]
	v_mfma_f32_16x16x32_bf16 v[74:77], v[190:193], v[232:235], v[74:77]
	v_mfma_f32_16x16x32_bf16 v[74:77], v[168:171], v[228:231], v[74:77]
	v_mfma_f32_16x16x32_bf16 v[90:93], v[168:171], v[202:205], v[90:93]
	v_mfma_f32_16x16x32_bf16 v[90:93], v[190:193], v[206:209], v[90:93]
	v_mfma_f32_16x16x32_bf16 v[106:109], v[190:193], v[198:201], v[106:109]
	v_mfma_f32_16x16x32_bf16 v[106:109], v[168:171], v[194:197], v[106:109]
	s_barrier
	s_setprio 0
.Lz0_0_0_ret:
	s_add_i32 s49, s49, s26
	v_lshl_add_u64 v[172:173], s[22:23], 0, v[0:1]
	s_mov_b32 m0, s49
	ds_read_b128 v[194:197], v147 offset:16384
	ds_read_b128 v[198:201], v147 offset:17408
	ds_read_b128 v[202:205], v147 offset:18432
	ds_read_b128 v[206:209], v147 offset:19456
	ds_read_b128 v[228:231], v147 offset:20480
	ds_read_b128 v[232:235], v147 offset:21504
	ds_read_b128 v[236:239], v147 offset:22528
	ds_read_b128 v[240:243], v147 offset:23552
	global_load_lds_dwordx4 v[172:173], off
	s_add_i32 m0, s49, 0x2000
	s_add_u32 s50, s22, 0x100000
	v_lshl_add_u64 v[178:179], s[22:23], 0, v[130:131]
	s_addc_u32 s51, s23, 0
	s_add_i32 s49, s52, s26
	global_load_lds_dwordx4 v[178:179], off
	v_lshl_add_u64 v[180:181], s[50:51], 0, v[0:1]
	s_mov_b32 m0, s49
	v_lshl_add_u64 v[210:211], s[24:25], 0, v[132:133]
	global_load_lds_dwordx4 v[180:181], off
	v_lshl_add_u64 v[180:181], s[50:51], 0, v[130:131]
	s_add_i32 m0, s49, 0x2000
	s_nop 0
	global_load_lds_dwordx4 v[180:181], off
	v_lshl_add_u64 v[180:181], s[24:25], 0, v[134:135]
	s_mov_b32 m0, s31
	s_nop 0
	global_load_lds_dwordx4 v[180:181], off
	s_mov_b32 m0, s36
	s_nop 0
	global_load_lds_dwordx4 v[210:211], off
	s_waitcnt vmcnt(8)
	s_waitcnt lgkmcnt(0)
	s_cmp_eq_u32 s48, -2
	s_cbranch_scc1 .Lz0_0_1
	s_setprio 1
	s_barrier
	v_mfma_f32_16x16x32_bf16 v[62:65], v[140:143], v[194:197], v[62:65]
	v_mfma_f32_16x16x32_bf16 v[62:65], v[148:151], v[198:201], v[62:65]
	v_mfma_f32_16x16x32_bf16 v[54:57], v[148:151], v[206:209], v[54:57]
	v_mfma_f32_16x16x32_bf16 v[54:57], v[140:143], v[202:205], v[54:57]
	v_mfma_f32_16x16x32_bf16 v[38:41], v[140:143], v[228:231], v[38:41]
	v_mfma_f32_16x16x32_bf16 v[38:41], v[148:151], v[232:235], v[38:41]
	v_mfma_f32_16x16x32_bf16 v[22:25], v[148:151], v[240:243], v[22:25]
	v_mfma_f32_16x16x32_bf16 v[22:25], v[140:143], v[236:239], v[22:25]
	v_mfma_f32_16x16x32_bf16 v[14:17], v[152:155], v[236:239], v[14:17]
	v_mfma_f32_16x16x32_bf16 v[14:17], v[156:159], v[240:243], v[14:17]
	v_mfma_f32_16x16x32_bf16 v[30:33], v[156:159], v[232:235], v[30:33]
	v_mfma_f32_16x16x32_bf16 v[30:33], v[152:155], v[228:231], v[30:33]
	v_mfma_f32_16x16x32_bf16 v[46:49], v[152:155], v[202:205], v[46:49]
	v_mfma_f32_16x16x32_bf16 v[46:49], v[156:159], v[206:209], v[46:49]
	v_mfma_f32_16x16x32_bf16 v[58:61], v[156:159], v[198:201], v[58:61]
	v_mfma_f32_16x16x32_bf16 v[58:61], v[152:155], v[194:197], v[58:61]
	v_mfma_f32_16x16x32_bf16 v[50:53], v[160:163], v[194:197], v[50:53]
	v_mfma_f32_16x16x32_bf16 v[50:53], v[164:167], v[198:201], v[50:53]
	v_mfma_f32_16x16x32_bf16 v[34:37], v[164:167], v[206:209], v[34:37]
	v_mfma_f32_16x16x32_bf16 v[34:37], v[160:163], v[202:205], v[34:37]
	v_mfma_f32_16x16x32_bf16 v[18:21], v[160:163], v[228:231], v[18:21]
	v_mfma_f32_16x16x32_bf16 v[18:21], v[164:167], v[232:235], v[18:21]
	v_mfma_f32_16x16x32_bf16 v[6:9], v[164:167], v[240:243], v[6:9]
	v_mfma_f32_16x16x32_bf16 v[6:9], v[160:163], v[236:239], v[6:9]
	v_mfma_f32_16x16x32_bf16 v[2:5], v[168:171], v[236:239], v[2:5]
	v_mfma_f32_16x16x32_bf16 v[2:5], v[190:193], v[240:243], v[2:5]
	v_mfma_f32_16x16x32_bf16 v[10:13], v[190:193], v[232:235], v[10:13]
	v_mfma_f32_16x16x32_bf16 v[10:13], v[168:171], v[228:231], v[10:13]
	v_mfma_f32_16x16x32_bf16 v[26:29], v[168:171], v[202:205], v[26:29]
	v_mfma_f32_16x16x32_bf16 v[26:29], v[190:193], v[206:209], v[26:29]
	v_mfma_f32_16x16x32_bf16 v[42:45], v[190:193], v[198:201], v[42:45]
	v_mfma_f32_16x16x32_bf16 v[42:45], v[168:171], v[194:197], v[42:45]
	s_barrier
	s_setprio 0
.Lz0_0_1_ret:
	s_add_i32 s49, 0, 0x18000
	s_add_i32 s50, 0, 0x1c000
	v_add_u32_e32 v156, s49, v145
	v_add_u32_e32 v175, s50, v145
	ds_read_b128 v[140:143], v156
	ds_read_b128 v[148:151], v156 offset:1024
	ds_read_b128 v[152:155], v156 offset:2048
	ds_read_b128 v[156:159], v156 offset:3072
	ds_read_b128 v[160:163], v175
	ds_read_b128 v[164:167], v175 offset:1024
	ds_read_b128 v[168:171], v175 offset:2048
	ds_read_b128 v[190:193], v175 offset:3072
	s_add_u32 s24, s24, 0x100000
	s_addc_u32 s25, s25, 0
	s_mov_b32 m0, s37
	v_lshl_add_u64 v[244:245], s[24:25], 0, v[134:135]
	ds_read_b128 v[194:197], v147 offset:32768
	ds_read_b128 v[198:201], v147 offset:33792
	ds_read_b128 v[202:205], v147 offset:34816
	ds_read_b128 v[206:209], v147 offset:35840
	ds_read_b128 v[228:231], v147 offset:36864
	ds_read_b128 v[232:235], v147 offset:37888
	ds_read_b128 v[236:239], v147 offset:38912
	ds_read_b128 v[240:243], v147 offset:39936
	global_load_lds_dwordx4 v[244:245], off
	v_lshl_add_u64 v[244:245], s[24:25], 0, v[132:133]
	s_mov_b32 m0, s38
	s_nop 0
	global_load_lds_dwordx4 v[244:245], off
	s_waitcnt vmcnt(8)
	s_waitcnt lgkmcnt(0)
	s_setprio 1
	s_barrier
	v_mfma_f32_16x16x32_bf16 v[126:129], v[140:143], v[194:197], v[126:129]
	v_mfma_f32_16x16x32_bf16 v[126:129], v[148:151], v[198:201], v[126:129]
	v_mfma_f32_16x16x32_bf16 v[118:121], v[148:151], v[206:209], v[118:121]
	v_mfma_f32_16x16x32_bf16 v[118:121], v[140:143], v[202:205], v[118:121]
	v_mfma_f32_16x16x32_bf16 v[102:105], v[140:143], v[228:231], v[102:105]
	v_mfma_f32_16x16x32_bf16 v[102:105], v[148:151], v[232:235], v[102:105]
	v_mfma_f32_16x16x32_bf16 v[86:89], v[148:151], v[240:243], v[86:89]
	v_mfma_f32_16x16x32_bf16 v[86:89], v[140:143], v[236:239], v[86:89]
	v_mfma_f32_16x16x32_bf16 v[78:81], v[152:155], v[236:239], v[78:81]
	v_mfma_f32_16x16x32_bf16 v[78:81], v[156:159], v[240:243], v[78:81]
	v_mfma_f32_16x16x32_bf16 v[94:97], v[156:159], v[232:235], v[94:97]
	v_mfma_f32_16x16x32_bf16 v[94:97], v[152:155], v[228:231], v[94:97]
	v_mfma_f32_16x16x32_bf16 v[110:113], v[152:155], v[202:205], v[110:113]
	v_mfma_f32_16x16x32_bf16 v[110:113], v[156:159], v[206:209], v[110:113]
	v_mfma_f32_16x16x32_bf16 v[122:125], v[156:159], v[198:201], v[122:125]
	v_mfma_f32_16x16x32_bf16 v[122:125], v[152:155], v[194:197], v[122:125]
	v_mfma_f32_16x16x32_bf16 v[114:117], v[160:163], v[194:197], v[114:117]
	v_mfma_f32_16x16x32_bf16 v[114:117], v[164:167], v[198:201], v[114:117]
	v_mfma_f32_16x16x32_bf16 v[98:101], v[164:167], v[206:209], v[98:101]
	v_mfma_f32_16x16x32_bf16 v[98:101], v[160:163], v[202:205], v[98:101]
	v_mfma_f32_16x16x32_bf16 v[82:85], v[160:163], v[228:231], v[82:85]
	v_mfma_f32_16x16x32_bf16 v[82:85], v[164:167], v[232:235], v[82:85]
	v_mfma_f32_16x16x32_bf16 v[70:73], v[164:167], v[240:243], v[70:73]
	v_mfma_f32_16x16x32_bf16 v[70:73], v[160:163], v[236:239], v[70:73]
	v_mfma_f32_16x16x32_bf16 v[66:69], v[168:171], v[236:239], v[66:69]
	v_mfma_f32_16x16x32_bf16 v[66:69], v[190:193], v[240:243], v[66:69]
	v_mfma_f32_16x16x32_bf16 v[74:77], v[190:193], v[232:235], v[74:77]
	v_mfma_f32_16x16x32_bf16 v[74:77], v[168:171], v[228:231], v[74:77]
	v_mfma_f32_16x16x32_bf16 v[90:93], v[168:171], v[202:205], v[90:93]
	v_mfma_f32_16x16x32_bf16 v[90:93], v[190:193], v[206:209], v[90:93]
	v_mfma_f32_16x16x32_bf16 v[106:109], v[190:193], v[198:201], v[106:109]
	v_mfma_f32_16x16x32_bf16 v[106:109], v[168:171], v[194:197], v[106:109]
	s_barrier
	s_setprio 0
	s_add_i32 s24, s49, s26
	v_lshl_add_u64 v[172:173], v[172:173], 0, s[34:35]
	s_mov_b32 m0, s24
	ds_read_b128 v[194:197], v147 offset:49152
	ds_read_b128 v[198:201], v147 offset:50176
	ds_read_b128 v[202:205], v147 offset:51200
	ds_read_b128 v[206:209], v147 offset:52224
	ds_read_b128 v[228:231], v147 offset:53248
	ds_read_b128 v[232:235], v147 offset:54272
	ds_read_b128 v[236:239], v147 offset:55296
	ds_read_b128 v[240:243], v147 offset:56320
	global_load_lds_dwordx4 v[172:173], off
	s_add_i32 m0, s24, 0x2000
	s_add_u32 s22, s22, 0x100080
	v_lshl_add_u64 v[172:173], v[178:179], 0, s[34:35]
	s_addc_u32 s23, s23, 0
	s_add_i32 s24, s50, s26
	global_load_lds_dwordx4 v[172:173], off
	v_lshl_add_u64 v[172:173], s[22:23], 0, v[0:1]
	s_mov_b32 m0, s24
	s_nop 0
	global_load_lds_dwordx4 v[172:173], off
	v_lshl_add_u64 v[172:173], s[22:23], 0, v[130:131]
	s_add_i32 m0, s24, 0x2000
	s_nop 0
	global_load_lds_dwordx4 v[172:173], off
	v_lshl_add_u64 v[172:173], v[180:181], 0, s[34:35]
	s_mov_b32 m0, s39
	s_nop 0
	global_load_lds_dwordx4 v[172:173], off
	v_lshl_add_u64 v[172:173], v[210:211], 0, s[34:35]
	s_mov_b32 m0, s40
	s_nop 0
	global_load_lds_dwordx4 v[172:173], off
	s_waitcnt vmcnt(8)
	s_waitcnt lgkmcnt(0)
	s_setprio 1
	s_barrier
	v_mfma_f32_16x16x32_bf16 v[62:65], v[140:143], v[194:197], v[62:65]
	v_mfma_f32_16x16x32_bf16 v[62:65], v[148:151], v[198:201], v[62:65]
	v_mfma_f32_16x16x32_bf16 v[54:57], v[148:151], v[206:209], v[54:57]
	v_mfma_f32_16x16x32_bf16 v[54:57], v[140:143], v[202:205], v[54:57]
	v_mfma_f32_16x16x32_bf16 v[38:41], v[140:143], v[228:231], v[38:41]
	v_mfma_f32_16x16x32_bf16 v[38:41], v[148:151], v[232:235], v[38:41]
	v_mfma_f32_16x16x32_bf16 v[22:25], v[148:151], v[240:243], v[22:25]
	v_mfma_f32_16x16x32_bf16 v[22:25], v[140:143], v[236:239], v[22:25]
	v_mfma_f32_16x16x32_bf16 v[14:17], v[152:155], v[236:239], v[14:17]
	v_mfma_f32_16x16x32_bf16 v[14:17], v[156:159], v[240:243], v[14:17]
	v_mfma_f32_16x16x32_bf16 v[30:33], v[156:159], v[232:235], v[30:33]
	v_mfma_f32_16x16x32_bf16 v[30:33], v[152:155], v[228:231], v[30:33]
	v_mfma_f32_16x16x32_bf16 v[46:49], v[152:155], v[202:205], v[46:49]
	v_mfma_f32_16x16x32_bf16 v[46:49], v[156:159], v[206:209], v[46:49]
	v_mfma_f32_16x16x32_bf16 v[58:61], v[156:159], v[198:201], v[58:61]
	v_mfma_f32_16x16x32_bf16 v[58:61], v[152:155], v[194:197], v[58:61]
	v_mfma_f32_16x16x32_bf16 v[50:53], v[160:163], v[194:197], v[50:53]
	v_mfma_f32_16x16x32_bf16 v[50:53], v[164:167], v[198:201], v[50:53]
	v_mfma_f32_16x16x32_bf16 v[34:37], v[164:167], v[206:209], v[34:37]
	v_mfma_f32_16x16x32_bf16 v[34:37], v[160:163], v[202:205], v[34:37]
	v_mfma_f32_16x16x32_bf16 v[18:21], v[160:163], v[228:231], v[18:21]
	v_mfma_f32_16x16x32_bf16 v[18:21], v[164:167], v[232:235], v[18:21]
	v_mfma_f32_16x16x32_bf16 v[6:9], v[164:167], v[240:243], v[6:9]
	v_mfma_f32_16x16x32_bf16 v[6:9], v[160:163], v[236:239], v[6:9]
	v_mfma_f32_16x16x32_bf16 v[2:5], v[168:171], v[236:239], v[2:5]
	v_mfma_f32_16x16x32_bf16 v[2:5], v[190:193], v[240:243], v[2:5]
	v_mfma_f32_16x16x32_bf16 v[10:13], v[190:193], v[232:235], v[10:13]
	v_mfma_f32_16x16x32_bf16 v[10:13], v[168:171], v[228:231], v[10:13]
	v_mfma_f32_16x16x32_bf16 v[26:29], v[168:171], v[202:205], v[26:29]
	v_mfma_f32_16x16x32_bf16 v[26:29], v[190:193], v[206:209], v[26:29]
	v_mfma_f32_16x16x32_bf16 v[42:45], v[190:193], v[198:201], v[42:45]
	v_mfma_f32_16x16x32_bf16 v[42:45], v[168:171], v[194:197], v[42:45]
	s_barrier
	s_setprio 0
	s_add_i32 s48, s48, 2
	s_add_u32 s18, s18, 0x100
	s_addc_u32 s19, s19, 0
	s_add_u32 s46, s46, 0x100
	s_addc_u32 s47, s47, 0
	s_cmp_gt_u32 s48, 61
	s_cbranch_scc0 .LBB0_139
	s_and_b64 vcc, exec, s[4:5]
	s_cbranch_vccz .LBB0_142
	s_barrier

.Lz0_0_0:
	s_setprio 1
	s_barrier
	v_mfma_f32_16x16x32_bf16 v[126:129], v[140:143], v[194:197], 0
	v_mfma_f32_16x16x32_bf16 v[126:129], v[148:151], v[198:201], v[126:129]
	v_mfma_f32_16x16x32_bf16 v[118:121], v[148:151], v[206:209], 0
	v_mfma_f32_16x16x32_bf16 v[118:121], v[140:143], v[202:205], v[118:121]
	v_mfma_f32_16x16x32_bf16 v[102:105], v[140:143], v[228:231], 0
	v_mfma_f32_16x16x32_bf16 v[102:105], v[148:151], v[232:235], v[102:105]
	v_mfma_f32_16x16x32_bf16 v[86:89], v[148:151], v[240:243], 0
	v_mfma_f32_16x16x32_bf16 v[86:89], v[140:143], v[236:239], v[86:89]
	v_mfma_f32_16x16x32_bf16 v[78:81], v[152:155], v[236:239], 0
	v_mfma_f32_16x16x32_bf16 v[78:81], v[156:159], v[240:243], v[78:81]
	v_mfma_f32_16x16x32_bf16 v[94:97], v[156:159], v[232:235], 0
	v_mfma_f32_16x16x32_bf16 v[94:97], v[152:155], v[228:231], v[94:97]
	v_mfma_f32_16x16x32_bf16 v[110:113], v[152:155], v[202:205], 0
	v_mfma_f32_16x16x32_bf16 v[110:113], v[156:159], v[206:209], v[110:113]
	v_mfma_f32_16x16x32_bf16 v[122:125], v[156:159], v[198:201], 0
	v_mfma_f32_16x16x32_bf16 v[122:125], v[152:155], v[194:197], v[122:125]
	v_mfma_f32_16x16x32_bf16 v[114:117], v[160:163], v[194:197], 0
	v_mfma_f32_16x16x32_bf16 v[114:117], v[164:167], v[198:201], v[114:117]
	v_mfma_f32_16x16x32_bf16 v[98:101], v[164:167], v[206:209], 0
	v_mfma_f32_16x16x32_bf16 v[98:101], v[160:163], v[202:205], v[98:101]
	v_mfma_f32_16x16x32_bf16 v[82:85], v[160:163], v[228:231], 0
	v_mfma_f32_16x16x32_bf16 v[82:85], v[164:167], v[232:235], v[82:85]
	v_mfma_f32_16x16x32_bf16 v[70:73], v[164:167], v[240:243], 0
	v_mfma_f32_16x16x32_bf16 v[70:73], v[160:163], v[236:239], v[70:73]
	v_mfma_f32_16x16x32_bf16 v[66:69], v[168:171], v[236:239], 0
	v_mfma_f32_16x16x32_bf16 v[66:69], v[190:193], v[240:243], v[66:69]
	v_mfma_f32_16x16x32_bf16 v[74:77], v[190:193], v[232:235], 0
	v_mfma_f32_16x16x32_bf16 v[74:77], v[168:171], v[228:231], v[74:77]
	v_mfma_f32_16x16x32_bf16 v[90:93], v[168:171], v[202:205], 0
	v_mfma_f32_16x16x32_bf16 v[90:93], v[190:193], v[206:209], v[90:93]
	v_mfma_f32_16x16x32_bf16 v[106:109], v[190:193], v[198:201], 0
	v_mfma_f32_16x16x32_bf16 v[106:109], v[168:171], v[194:197], v[106:109]
	s_barrier
	s_setprio 0
	s_branch .Lz0_0_0_ret
.Lz0_0_1:
	s_setprio 1
	s_barrier
	v_mfma_f32_16x16x32_bf16 v[62:65], v[140:143], v[194:197], 0
	v_mfma_f32_16x16x32_bf16 v[62:65], v[148:151], v[198:201], v[62:65]
	v_mfma_f32_16x16x32_bf16 v[54:57], v[148:151], v[206:209], 0
	v_mfma_f32_16x16x32_bf16 v[54:57], v[140:143], v[202:205], v[54:57]
	v_mfma_f32_16x16x32_bf16 v[38:41], v[140:143], v[228:231], 0
	v_mfma_f32_16x16x32_bf16 v[38:41], v[148:151], v[232:235], v[38:41]
	v_mfma_f32_16x16x32_bf16 v[22:25], v[148:151], v[240:243], 0
	v_mfma_f32_16x16x32_bf16 v[22:25], v[140:143], v[236:239], v[22:25]
	v_mfma_f32_16x16x32_bf16 v[14:17], v[152:155], v[236:239], 0
	v_mfma_f32_16x16x32_bf16 v[14:17], v[156:159], v[240:243], v[14:17]
	v_mfma_f32_16x16x32_bf16 v[30:33], v[156:159], v[232:235], 0
	v_mfma_f32_16x16x32_bf16 v[30:33], v[152:155], v[228:231], v[30:33]
	v_mfma_f32_16x16x32_bf16 v[46:49], v[152:155], v[202:205], 0
	v_mfma_f32_16x16x32_bf16 v[46:49], v[156:159], v[206:209], v[46:49]
	v_mfma_f32_16x16x32_bf16 v[58:61], v[156:159], v[198:201], 0
	v_mfma_f32_16x16x32_bf16 v[58:61], v[152:155], v[194:197], v[58:61]
	v_mfma_f32_16x16x32_bf16 v[50:53], v[160:163], v[194:197], 0
	v_mfma_f32_16x16x32_bf16 v[50:53], v[164:167], v[198:201], v[50:53]
	v_mfma_f32_16x16x32_bf16 v[34:37], v[164:167], v[206:209], 0
	v_mfma_f32_16x16x32_bf16 v[34:37], v[160:163], v[202:205], v[34:37]
	v_mfma_f32_16x16x32_bf16 v[18:21], v[160:163], v[228:231], 0
	v_mfma_f32_16x16x32_bf16 v[18:21], v[164:167], v[232:235], v[18:21]
	v_mfma_f32_16x16x32_bf16 v[6:9], v[164:167], v[240:243], 0
	v_mfma_f32_16x16x32_bf16 v[6:9], v[160:163], v[236:239], v[6:9]
	v_mfma_f32_16x16x32_bf16 v[2:5], v[168:171], v[236:239], 0
	v_mfma_f32_16x16x32_bf16 v[2:5], v[190:193], v[240:243], v[2:5]
	v_mfma_f32_16x16x32_bf16 v[10:13], v[190:193], v[232:235], 0
	v_mfma_f32_16x16x32_bf16 v[10:13], v[168:171], v[228:231], v[10:13]
	v_mfma_f32_16x16x32_bf16 v[26:29], v[168:171], v[202:205], 0
	v_mfma_f32_16x16x32_bf16 v[26:29], v[190:193], v[206:209], v[26:29]
	v_mfma_f32_16x16x32_bf16 v[42:45], v[190:193], v[198:201], 0
	v_mfma_f32_16x16x32_bf16 v[42:45], v[168:171], v[194:197], v[42:45]
	s_barrier
	s_setprio 0
	s_branch .Lz0_0_1_ret

.LBB0_574:
	s_ashr_i32 s9, s8, 31
	s_lshl_b64 s[14:15], s[8:9], 21
	v_readlane_b32 s7, v254, 15
	s_add_u32 s14, s7, s14
	v_readlane_b32 s7, v254, 16
	s_addc_u32 s15, s7, s15
	s_and_b64 s[16:17], s[0:1], exec
	s_cselect_b32 s9, s15, s19
	s_cselect_b32 s48, s14, s18
	s_ashr_i32 s7, s6, 31
	s_lshl_b64 s[16:17], s[6:7], 21
	s_add_u32 s16, s26, s16
	s_addc_u32 s17, s31, s17
	s_and_b64 s[24:25], s[0:1], exec
	s_cselect_b32 s7, s17, s23
	s_cselect_b32 s49, s16, s22
	s_add_u32 s18, s18, 0x100080
	s_addc_u32 s19, s19, 0
	s_add_u32 s50, s22, 0x100
	s_addc_u32 s51, s23, 0
	s_mov_b32 s52, -2
.LBB0_575:
	s_add_u32 s22, s18, 0xfff00080
	s_addc_u32 s23, s19, -1
	s_add_i32 s53, 0, 0x10000
	s_cmp_eq_u32 s52, 60
	s_cselect_b32 s25, s9, s23
	s_cselect_b32 s24, s48, s22
	v_add_u32_e32 v140, s53, v143
	s_cselect_b32 s23, s7, s51
	s_cselect_b32 s22, s49, s50
	s_add_i32 s56, 0, 0x14000
	ds_read_b128 v[146:149], v140
	ds_read_b128 v[150:153], v140 offset:1024
	ds_read_b128 v[154:157], v140 offset:2048
	ds_read_b128 v[158:161], v140 offset:3072
	v_add_u32_e32 v140, s56, v143
	ds_read_b128 v[162:165], v140
	ds_read_b128 v[166:169], v140 offset:1024
	ds_read_b128 v[170:173], v140 offset:2048
	ds_read_b128 v[178:181], v140 offset:3072
	v_lshl_add_u64 v[140:141], s[18:19], 0, v[136:137]
	s_add_i32 m0, s39, 0xc000
	ds_read_b128 v[190:193], v145
	ds_read_b128 v[194:197], v145 offset:1024
	ds_read_b128 v[198:201], v145 offset:2048
	ds_read_b128 v[202:205], v145 offset:3072
	ds_read_b128 v[206:209], v145 offset:4096
	ds_read_b128 v[228:231], v145 offset:5120
	ds_read_b128 v[232:235], v145 offset:6144
	ds_read_b128 v[236:239], v145 offset:7168
	global_load_lds_dwordx4 v[140:141], off
	v_lshl_add_u64 v[140:141], s[18:19], 0, v[138:139]
	s_add_i32 m0, s39, 0xe000
	s_nop 0
	global_load_lds_dwordx4 v[140:141], off
	s_waitcnt vmcnt(8)
	s_waitcnt lgkmcnt(0)
	s_cmp_eq_u32 s52, -2
	s_cbranch_scc1 .Lz0_1_0
	s_setprio 1
	s_barrier
	v_mfma_f32_16x16x32_bf16 v[126:129], v[146:149], v[190:193], v[126:129]
	v_mfma_f32_16x16x32_bf16 v[126:129], v[150:153], v[194:197], v[126:129]
	v_mfma_f32_16x16x32_bf16 v[118:121], v[150:153], v[202:205], v[118:121]
	v_mfma_f32_16x16x32_bf16 v[118:121], v[146:149], v[198:201], v[118:121]
	v_mfma_f32_16x16x32_bf16 v[102:105], v[146:149], v[206:209], v[102:105]
	v_mfma_f32_16x16x32_bf16 v[102:105], v[150:153], v[228:231], v[102:105]
	v_mfma_f32_16x16x32_bf16 v[86:89], v[150:153], v[236:239], v[86:89]
	v_mfma_f32_16x16x32_bf16 v[86:89], v[146:149], v[232:235], v[86:89]
	v_mfma_f32_16x16x32_bf16 v[78:81], v[154:157], v[232:235], v[78:81]
	v_mfma_f32_16x16x32_bf16 v[78:81], v[158:161], v[236:239], v[78:81]
	v_mfma_f32_16x16x32_bf16 v[94:97], v[158:161], v[228:231], v[94:97]
	v_mfma_f32_16x16x32_bf16 v[94:97], v[154:157], v[206:209], v[94:97]
	v_mfma_f32_16x16x32_bf16 v[110:113], v[154:157], v[198:201], v[110:113]
	v_mfma_f32_16x16x32_bf16 v[110:113], v[158:161], v[202:205], v[110:113]
	v_mfma_f32_16x16x32_bf16 v[122:125], v[158:161], v[194:197], v[122:125]
	v_mfma_f32_16x16x32_bf16 v[122:125], v[154:157], v[190:193], v[122:125]
	v_mfma_f32_16x16x32_bf16 v[114:117], v[162:165], v[190:193], v[114:117]
	v_mfma_f32_16x16x32_bf16 v[114:117], v[166:169], v[194:197], v[114:117]
	v_mfma_f32_16x16x32_bf16 v[98:101], v[166:169], v[202:205], v[98:101]
	v_mfma_f32_16x16x32_bf16 v[98:101], v[162:165], v[198:201], v[98:101]
	v_mfma_f32_16x16x32_bf16 v[82:85], v[162:165], v[206:209], v[82:85]
	v_mfma_f32_16x16x32_bf16 v[82:85], v[166:169], v[228:231], v[82:85]
	v_mfma_f32_16x16x32_bf16 v[70:73], v[166:169], v[236:239], v[70:73]
	v_mfma_f32_16x16x32_bf16 v[70:73], v[162:165], v[232:235], v[70:73]
	v_mfma_f32_16x16x32_bf16 v[66:69], v[170:173], v[232:235], v[66:69]
	v_mfma_f32_16x16x32_bf16 v[66:69], v[178:181], v[236:239], v[66:69]
	v_mfma_f32_16x16x32_bf16 v[74:77], v[178:181], v[228:231], v[74:77]
	v_mfma_f32_16x16x32_bf16 v[74:77], v[170:173], v[206:209], v[74:77]
	v_mfma_f32_16x16x32_bf16 v[90:93], v[170:173], v[198:201], v[90:93]
	v_mfma_f32_16x16x32_bf16 v[90:93], v[178:181], v[202:205], v[90:93]
	v_mfma_f32_16x16x32_bf16 v[106:109], v[178:181], v[194:197], v[106:109]
	v_mfma_f32_16x16x32_bf16 v[106:109], v[170:173], v[190:193], v[106:109]
	s_barrier
	s_setprio 0
.Lz0_1_0_ret:
	s_add_i32 s53, s53, s38
	v_lshl_add_u64 v[140:141], s[22:23], 0, v[0:1]
	s_mov_b32 m0, s53
	ds_read_b128 v[190:193], v145 offset:16384
	ds_read_b128 v[194:197], v145 offset:17408
	ds_read_b128 v[198:201], v145 offset:18432
	ds_read_b128 v[202:205], v145 offset:19456
	ds_read_b128 v[206:209], v145 offset:20480
	ds_read_b128 v[228:231], v145 offset:21504
	ds_read_b128 v[232:235], v145 offset:22528
	ds_read_b128 v[236:239], v145 offset:23552
	global_load_lds_dwordx4 v[140:141], off
	s_add_i32 m0, s53, 0x2000
	s_add_u32 s54, s22, 0x100000
	v_lshl_add_u64 v[186:187], s[22:23], 0, v[130:131]
	s_addc_u32 s55, s23, 0
	s_add_i32 s53, s56, s38
	global_load_lds_dwordx4 v[186:187], off
	v_lshl_add_u64 v[188:189], s[54:55], 0, v[0:1]
	s_mov_b32 m0, s53
	v_lshl_add_u64 v[210:211], s[24:25], 0, v[132:133]
	global_load_lds_dwordx4 v[188:189], off
	v_lshl_add_u64 v[188:189], s[54:55], 0, v[130:131]
	s_add_i32 m0, s53, 0x2000
	s_nop 0
	global_load_lds_dwordx4 v[188:189], off
	v_lshl_add_u64 v[188:189], s[24:25], 0, v[134:135]
	s_mov_b32 m0, s39
	s_nop 0
	global_load_lds_dwordx4 v[188:189], off
	s_mov_b32 m0, s40
	s_nop 0
	global_load_lds_dwordx4 v[210:211], off
	s_waitcnt vmcnt(8)
	s_waitcnt lgkmcnt(0)
	s_cmp_eq_u32 s52, -2
	s_cbranch_scc1 .Lz0_1_1
	s_setprio 1
	s_barrier
	v_mfma_f32_16x16x32_bf16 v[62:65], v[146:149], v[190:193], v[62:65]
	v_mfma_f32_16x16x32_bf16 v[62:65], v[150:153], v[194:197], v[62:65]
	v_mfma_f32_16x16x32_bf16 v[54:57], v[150:153], v[202:205], v[54:57]
	v_mfma_f32_16x16x32_bf16 v[54:57], v[146:149], v[198:201], v[54:57]
	v_mfma_f32_16x16x32_bf16 v[38:41], v[146:149], v[206:209], v[38:41]
	v_mfma_f32_16x16x32_bf16 v[38:41], v[150:153], v[228:231], v[38:41]
	v_mfma_f32_16x16x32_bf16 v[22:25], v[150:153], v[236:239], v[22:25]
	v_mfma_f32_16x16x32_bf16 v[22:25], v[146:149], v[232:235], v[22:25]
	v_mfma_f32_16x16x32_bf16 v[14:17], v[154:157], v[232:235], v[14:17]
	v_mfma_f32_16x16x32_bf16 v[14:17], v[158:161], v[236:239], v[14:17]
	v_mfma_f32_16x16x32_bf16 v[30:33], v[158:161], v[228:231], v[30:33]
	v_mfma_f32_16x16x32_bf16 v[30:33], v[154:157], v[206:209], v[30:33]
	v_mfma_f32_16x16x32_bf16 v[46:49], v[154:157], v[198:201], v[46:49]
	v_mfma_f32_16x16x32_bf16 v[46:49], v[158:161], v[202:205], v[46:49]
	v_mfma_f32_16x16x32_bf16 v[58:61], v[158:161], v[194:197], v[58:61]
	v_mfma_f32_16x16x32_bf16 v[58:61], v[154:157], v[190:193], v[58:61]
	v_mfma_f32_16x16x32_bf16 v[50:53], v[162:165], v[190:193], v[50:53]
	v_mfma_f32_16x16x32_bf16 v[50:53], v[166:169], v[194:197], v[50:53]
	v_mfma_f32_16x16x32_bf16 v[34:37], v[166:169], v[202:205], v[34:37]
	v_mfma_f32_16x16x32_bf16 v[34:37], v[162:165], v[198:201], v[34:37]
	v_mfma_f32_16x16x32_bf16 v[18:21], v[162:165], v[206:209], v[18:21]
	v_mfma_f32_16x16x32_bf16 v[18:21], v[166:169], v[228:231], v[18:21]
	v_mfma_f32_16x16x32_bf16 v[6:9], v[166:169], v[236:239], v[6:9]
	v_mfma_f32_16x16x32_bf16 v[6:9], v[162:165], v[232:235], v[6:9]
	v_mfma_f32_16x16x32_bf16 v[2:5], v[170:173], v[232:235], v[2:5]
	v_mfma_f32_16x16x32_bf16 v[2:5], v[178:181], v[236:239], v[2:5]
	v_mfma_f32_16x16x32_bf16 v[10:13], v[178:181], v[228:231], v[10:13]
	v_mfma_f32_16x16x32_bf16 v[10:13], v[170:173], v[206:209], v[10:13]
	v_mfma_f32_16x16x32_bf16 v[26:29], v[170:173], v[198:201], v[26:29]
	v_mfma_f32_16x16x32_bf16 v[26:29], v[178:181], v[202:205], v[26:29]
	v_mfma_f32_16x16x32_bf16 v[42:45], v[178:181], v[194:197], v[42:45]
	v_mfma_f32_16x16x32_bf16 v[42:45], v[170:173], v[190:193], v[42:45]
	s_barrier
	s_setprio 0
.Lz0_1_1_ret:
	s_add_i32 s53, 0, 0x18000
	s_add_i32 s54, 0, 0x1c000
	v_add_u32_e32 v158, s53, v143
	v_add_u32_e32 v175, s54, v143
	ds_read_b128 v[146:149], v158
	ds_read_b128 v[150:153], v158 offset:1024
	ds_read_b128 v[154:157], v158 offset:2048
	ds_read_b128 v[158:161], v158 offset:3072
	ds_read_b128 v[162:165], v175
	ds_read_b128 v[166:169], v175 offset:1024
	ds_read_b128 v[170:173], v175 offset:2048
	ds_read_b128 v[178:181], v175 offset:3072
	s_add_u32 s24, s24, 0x100000
	s_addc_u32 s25, s25, 0
	s_mov_b32 m0, s41
	v_lshl_add_u64 v[226:227], s[24:25], 0, v[134:135]
	ds_read_b128 v[190:193], v145 offset:32768
	ds_read_b128 v[194:197], v145 offset:33792
	ds_read_b128 v[198:201], v145 offset:34816
	ds_read_b128 v[202:205], v145 offset:35840
	ds_read_b128 v[206:209], v145 offset:36864
	ds_read_b128 v[228:231], v145 offset:37888
	ds_read_b128 v[232:235], v145 offset:38912
	ds_read_b128 v[236:239], v145 offset:39936
	global_load_lds_dwordx4 v[226:227], off
	v_lshl_add_u64 v[226:227], s[24:25], 0, v[132:133]
	s_mov_b32 m0, s42
	s_nop 0
	global_load_lds_dwordx4 v[226:227], off
	s_waitcnt vmcnt(8)
	s_waitcnt lgkmcnt(0)
	s_setprio 1
	s_barrier
	v_mfma_f32_16x16x32_bf16 v[126:129], v[146:149], v[190:193], v[126:129]
	v_mfma_f32_16x16x32_bf16 v[126:129], v[150:153], v[194:197], v[126:129]
	v_mfma_f32_16x16x32_bf16 v[118:121], v[150:153], v[202:205], v[118:121]
	v_mfma_f32_16x16x32_bf16 v[118:121], v[146:149], v[198:201], v[118:121]
	v_mfma_f32_16x16x32_bf16 v[102:105], v[146:149], v[206:209], v[102:105]
	v_mfma_f32_16x16x32_bf16 v[102:105], v[150:153], v[228:231], v[102:105]
	v_mfma_f32_16x16x32_bf16 v[86:89], v[150:153], v[236:239], v[86:89]
	v_mfma_f32_16x16x32_bf16 v[86:89], v[146:149], v[232:235], v[86:89]
	v_mfma_f32_16x16x32_bf16 v[78:81], v[154:157], v[232:235], v[78:81]
	v_mfma_f32_16x16x32_bf16 v[78:81], v[158:161], v[236:239], v[78:81]
	v_mfma_f32_16x16x32_bf16 v[94:97], v[158:161], v[228:231], v[94:97]
	v_mfma_f32_16x16x32_bf16 v[94:97], v[154:157], v[206:209], v[94:97]
	v_mfma_f32_16x16x32_bf16 v[110:113], v[154:157], v[198:201], v[110:113]
	v_mfma_f32_16x16x32_bf16 v[110:113], v[158:161], v[202:205], v[110:113]
	v_mfma_f32_16x16x32_bf16 v[122:125], v[158:161], v[194:197], v[122:125]
	v_mfma_f32_16x16x32_bf16 v[122:125], v[154:157], v[190:193], v[122:125]
	v_mfma_f32_16x16x32_bf16 v[114:117], v[162:165], v[190:193], v[114:117]
	v_mfma_f32_16x16x32_bf16 v[114:117], v[166:169], v[194:197], v[114:117]
	v_mfma_f32_16x16x32_bf16 v[98:101], v[166:169], v[202:205], v[98:101]
	v_mfma_f32_16x16x32_bf16 v[98:101], v[162:165], v[198:201], v[98:101]
	v_mfma_f32_16x16x32_bf16 v[82:85], v[162:165], v[206:209], v[82:85]
	v_mfma_f32_16x16x32_bf16 v[82:85], v[166:169], v[228:231], v[82:85]
	v_mfma_f32_16x16x32_bf16 v[70:73], v[166:169], v[236:239], v[70:73]
	v_mfma_f32_16x16x32_bf16 v[70:73], v[162:165], v[232:235], v[70:73]
	v_mfma_f32_16x16x32_bf16 v[66:69], v[170:173], v[232:235], v[66:69]
	v_mfma_f32_16x16x32_bf16 v[66:69], v[178:181], v[236:239], v[66:69]
	v_mfma_f32_16x16x32_bf16 v[74:77], v[178:181], v[228:231], v[74:77]
	v_mfma_f32_16x16x32_bf16 v[74:77], v[170:173], v[206:209], v[74:77]
	v_mfma_f32_16x16x32_bf16 v[90:93], v[170:173], v[198:201], v[90:93]
	v_mfma_f32_16x16x32_bf16 v[90:93], v[178:181], v[202:205], v[90:93]
	v_mfma_f32_16x16x32_bf16 v[106:109], v[178:181], v[194:197], v[106:109]
	v_mfma_f32_16x16x32_bf16 v[106:109], v[170:173], v[190:193], v[106:109]
	s_barrier
	s_setprio 0
	s_add_i32 s24, s53, s38
	v_lshl_add_u64 v[140:141], v[140:141], 0, s[34:35]
	s_mov_b32 m0, s24
	ds_read_b128 v[190:193], v145 offset:49152
	ds_read_b128 v[194:197], v145 offset:50176
	ds_read_b128 v[198:201], v145 offset:51200
	ds_read_b128 v[202:205], v145 offset:52224
	ds_read_b128 v[206:209], v145 offset:53248
	ds_read_b128 v[228:231], v145 offset:54272
	ds_read_b128 v[232:235], v145 offset:55296
	ds_read_b128 v[236:239], v145 offset:56320
	global_load_lds_dwordx4 v[140:141], off
	s_add_i32 m0, s24, 0x2000
	s_add_u32 s22, s22, 0x100080
	v_lshl_add_u64 v[140:141], v[186:187], 0, s[34:35]
	s_addc_u32 s23, s23, 0
	s_add_i32 s24, s54, s38
	global_load_lds_dwordx4 v[140:141], off
	v_lshl_add_u64 v[140:141], s[22:23], 0, v[0:1]
	s_mov_b32 m0, s24
	s_nop 0
	global_load_lds_dwordx4 v[140:141], off
	v_lshl_add_u64 v[140:141], s[22:23], 0, v[130:131]
	s_add_i32 m0, s24, 0x2000
	s_nop 0
	global_load_lds_dwordx4 v[140:141], off
	v_lshl_add_u64 v[140:141], v[188:189], 0, s[34:35]
	s_mov_b32 m0, s43
	s_nop 0
	global_load_lds_dwordx4 v[140:141], off
	v_lshl_add_u64 v[140:141], v[210:211], 0, s[34:35]
	s_mov_b32 m0, s44
	s_nop 0
	global_load_lds_dwordx4 v[140:141], off
	s_waitcnt vmcnt(8)
	s_waitcnt lgkmcnt(0)
	s_setprio 1
	s_barrier
	v_mfma_f32_16x16x32_bf16 v[62:65], v[146:149], v[190:193], v[62:65]
	v_mfma_f32_16x16x32_bf16 v[62:65], v[150:153], v[194:197], v[62:65]
	v_mfma_f32_16x16x32_bf16 v[54:57], v[150:153], v[202:205], v[54:57]
	v_mfma_f32_16x16x32_bf16 v[54:57], v[146:149], v[198:201], v[54:57]
	v_mfma_f32_16x16x32_bf16 v[38:41], v[146:149], v[206:209], v[38:41]
	v_mfma_f32_16x16x32_bf16 v[38:41], v[150:153], v[228:231], v[38:41]
	v_mfma_f32_16x16x32_bf16 v[22:25], v[150:153], v[236:239], v[22:25]
	v_mfma_f32_16x16x32_bf16 v[22:25], v[146:149], v[232:235], v[22:25]
	v_mfma_f32_16x16x32_bf16 v[14:17], v[154:157], v[232:235], v[14:17]
	v_mfma_f32_16x16x32_bf16 v[14:17], v[158:161], v[236:239], v[14:17]
	v_mfma_f32_16x16x32_bf16 v[30:33], v[158:161], v[228:231], v[30:33]
	v_mfma_f32_16x16x32_bf16 v[30:33], v[154:157], v[206:209], v[30:33]
	v_mfma_f32_16x16x32_bf16 v[46:49], v[154:157], v[198:201], v[46:49]
	v_mfma_f32_16x16x32_bf16 v[46:49], v[158:161], v[202:205], v[46:49]
	v_mfma_f32_16x16x32_bf16 v[58:61], v[158:161], v[194:197], v[58:61]
	v_mfma_f32_16x16x32_bf16 v[58:61], v[154:157], v[190:193], v[58:61]
	v_mfma_f32_16x16x32_bf16 v[50:53], v[162:165], v[190:193], v[50:53]
	v_mfma_f32_16x16x32_bf16 v[50:53], v[166:169], v[194:197], v[50:53]
	v_mfma_f32_16x16x32_bf16 v[34:37], v[166:169], v[202:205], v[34:37]
	v_mfma_f32_16x16x32_bf16 v[34:37], v[162:165], v[198:201], v[34:37]
	v_mfma_f32_16x16x32_bf16 v[18:21], v[162:165], v[206:209], v[18:21]
	v_mfma_f32_16x16x32_bf16 v[18:21], v[166:169], v[228:231], v[18:21]
	v_mfma_f32_16x16x32_bf16 v[6:9], v[166:169], v[236:239], v[6:9]
	v_mfma_f32_16x16x32_bf16 v[6:9], v[162:165], v[232:235], v[6:9]
	v_mfma_f32_16x16x32_bf16 v[2:5], v[170:173], v[232:235], v[2:5]
	v_mfma_f32_16x16x32_bf16 v[2:5], v[178:181], v[236:239], v[2:5]
	v_mfma_f32_16x16x32_bf16 v[10:13], v[178:181], v[228:231], v[10:13]
	v_mfma_f32_16x16x32_bf16 v[10:13], v[170:173], v[206:209], v[10:13]
	v_mfma_f32_16x16x32_bf16 v[26:29], v[170:173], v[198:201], v[26:29]
	v_mfma_f32_16x16x32_bf16 v[26:29], v[178:181], v[202:205], v[26:29]
	v_mfma_f32_16x16x32_bf16 v[42:45], v[178:181], v[194:197], v[42:45]
	v_mfma_f32_16x16x32_bf16 v[42:45], v[170:173], v[190:193], v[42:45]
	s_barrier
	s_setprio 0
	s_add_i32 s52, s52, 2
	s_add_u32 s18, s18, 0x100
	s_addc_u32 s19, s19, 0
	s_add_u32 s50, s50, 0x100
	s_addc_u32 s51, s51, 0
	s_cmp_gt_u32 s52, 61
	s_cbranch_scc0 .LBB0_575
	s_and_b64 vcc, exec, s[4:5]
	s_cbranch_vccz .LBB0_578
	s_barrier

.Lz0_1_0:
	s_setprio 1
	s_barrier
	v_mfma_f32_16x16x32_bf16 v[126:129], v[146:149], v[190:193], 0
	v_mfma_f32_16x16x32_bf16 v[126:129], v[150:153], v[194:197], v[126:129]
	v_mfma_f32_16x16x32_bf16 v[118:121], v[150:153], v[202:205], 0
	v_mfma_f32_16x16x32_bf16 v[118:121], v[146:149], v[198:201], v[118:121]
	v_mfma_f32_16x16x32_bf16 v[102:105], v[146:149], v[206:209], 0
	v_mfma_f32_16x16x32_bf16 v[102:105], v[150:153], v[228:231], v[102:105]
	v_mfma_f32_16x16x32_bf16 v[86:89], v[150:153], v[236:239], 0
	v_mfma_f32_16x16x32_bf16 v[86:89], v[146:149], v[232:235], v[86:89]
	v_mfma_f32_16x16x32_bf16 v[78:81], v[154:157], v[232:235], 0
	v_mfma_f32_16x16x32_bf16 v[78:81], v[158:161], v[236:239], v[78:81]
	v_mfma_f32_16x16x32_bf16 v[94:97], v[158:161], v[228:231], 0
	v_mfma_f32_16x16x32_bf16 v[94:97], v[154:157], v[206:209], v[94:97]
	v_mfma_f32_16x16x32_bf16 v[110:113], v[154:157], v[198:201], 0
	v_mfma_f32_16x16x32_bf16 v[110:113], v[158:161], v[202:205], v[110:113]
	v_mfma_f32_16x16x32_bf16 v[122:125], v[158:161], v[194:197], 0
	v_mfma_f32_16x16x32_bf16 v[122:125], v[154:157], v[190:193], v[122:125]
	v_mfma_f32_16x16x32_bf16 v[114:117], v[162:165], v[190:193], 0
	v_mfma_f32_16x16x32_bf16 v[114:117], v[166:169], v[194:197], v[114:117]
	v_mfma_f32_16x16x32_bf16 v[98:101], v[166:169], v[202:205], 0
	v_mfma_f32_16x16x32_bf16 v[98:101], v[162:165], v[198:201], v[98:101]
	v_mfma_f32_16x16x32_bf16 v[82:85], v[162:165], v[206:209], 0
	v_mfma_f32_16x16x32_bf16 v[82:85], v[166:169], v[228:231], v[82:85]
	v_mfma_f32_16x16x32_bf16 v[70:73], v[166:169], v[236:239], 0
	v_mfma_f32_16x16x32_bf16 v[70:73], v[162:165], v[232:235], v[70:73]
	v_mfma_f32_16x16x32_bf16 v[66:69], v[170:173], v[232:235], 0
	v_mfma_f32_16x16x32_bf16 v[66:69], v[178:181], v[236:239], v[66:69]
	v_mfma_f32_16x16x32_bf16 v[74:77], v[178:181], v[228:231], 0
	v_mfma_f32_16x16x32_bf16 v[74:77], v[170:173], v[206:209], v[74:77]
	v_mfma_f32_16x16x32_bf16 v[90:93], v[170:173], v[198:201], 0
	v_mfma_f32_16x16x32_bf16 v[90:93], v[178:181], v[202:205], v[90:93]
	v_mfma_f32_16x16x32_bf16 v[106:109], v[178:181], v[194:197], 0
	v_mfma_f32_16x16x32_bf16 v[106:109], v[170:173], v[190:193], v[106:109]
	s_barrier
	s_setprio 0
	s_branch .Lz0_1_0_ret
.Lz0_1_1:
	s_setprio 1
	s_barrier
	v_mfma_f32_16x16x32_bf16 v[62:65], v[146:149], v[190:193], 0
	v_mfma_f32_16x16x32_bf16 v[62:65], v[150:153], v[194:197], v[62:65]
	v_mfma_f32_16x16x32_bf16 v[54:57], v[150:153], v[202:205], 0
	v_mfma_f32_16x16x32_bf16 v[54:57], v[146:149], v[198:201], v[54:57]
	v_mfma_f32_16x16x32_bf16 v[38:41], v[146:149], v[206:209], 0
	v_mfma_f32_16x16x32_bf16 v[38:41], v[150:153], v[228:231], v[38:41]
	v_mfma_f32_16x16x32_bf16 v[22:25], v[150:153], v[236:239], 0
	v_mfma_f32_16x16x32_bf16 v[22:25], v[146:149], v[232:235], v[22:25]
	v_mfma_f32_16x16x32_bf16 v[14:17], v[154:157], v[232:235], 0
	v_mfma_f32_16x16x32_bf16 v[14:17], v[158:161], v[236:239], v[14:17]
	v_mfma_f32_16x16x32_bf16 v[30:33], v[158:161], v[228:231], 0
	v_mfma_f32_16x16x32_bf16 v[30:33], v[154:157], v[206:209], v[30:33]
	v_mfma_f32_16x16x32_bf16 v[46:49], v[154:157], v[198:201], 0
	v_mfma_f32_16x16x32_bf16 v[46:49], v[158:161], v[202:205], v[46:49]
	v_mfma_f32_16x16x32_bf16 v[58:61], v[158:161], v[194:197], 0
	v_mfma_f32_16x16x32_bf16 v[58:61], v[154:157], v[190:193], v[58:61]
	v_mfma_f32_16x16x32_bf16 v[50:53], v[162:165], v[190:193], 0
	v_mfma_f32_16x16x32_bf16 v[50:53], v[166:169], v[194:197], v[50:53]
	v_mfma_f32_16x16x32_bf16 v[34:37], v[166:169], v[202:205], 0
	v_mfma_f32_16x16x32_bf16 v[34:37], v[162:165], v[198:201], v[34:37]
	v_mfma_f32_16x16x32_bf16 v[18:21], v[162:165], v[206:209], 0
	v_mfma_f32_16x16x32_bf16 v[18:21], v[166:169], v[228:231], v[18:21]
	v_mfma_f32_16x16x32_bf16 v[6:9], v[166:169], v[236:239], 0
	v_mfma_f32_16x16x32_bf16 v[6:9], v[162:165], v[232:235], v[6:9]
	v_mfma_f32_16x16x32_bf16 v[2:5], v[170:173], v[232:235], 0
	v_mfma_f32_16x16x32_bf16 v[2:5], v[178:181], v[236:239], v[2:5]
	v_mfma_f32_16x16x32_bf16 v[10:13], v[178:181], v[228:231], 0
	v_mfma_f32_16x16x32_bf16 v[10:13], v[170:173], v[206:209], v[10:13]
	v_mfma_f32_16x16x32_bf16 v[26:29], v[170:173], v[198:201], 0
	v_mfma_f32_16x16x32_bf16 v[26:29], v[178:181], v[202:205], v[26:29]
	v_mfma_f32_16x16x32_bf16 v[42:45], v[178:181], v[194:197], 0
	v_mfma_f32_16x16x32_bf16 v[42:45], v[170:173], v[190:193], v[42:45]
	s_barrier
	s_setprio 0
	s_branch .Lz0_1_1_ret

.LBB0_720:
	s_ashr_i32 s7, s6, 31
	s_lshl_b64 s[8:9], s[6:7], 21
	s_add_u32 s8, s88, s8
	s_addc_u32 s9, s89, s9
	s_and_b64 s[14:15], s[38:39], exec
	s_cselect_b32 s7, s9, s17
	s_cselect_b32 s48, s8, s16
	s_ashr_i32 s5, s4, 31
	s_lshl_b64 s[14:15], s[4:5], 21
	s_add_u32 s14, s24, s14
	s_addc_u32 s15, s25, s15
	s_and_b64 s[22:23], s[38:39], exec
	s_cselect_b32 s5, s15, s19
	s_cselect_b32 s49, s14, s18
	s_add_u32 s16, s16, 0x100080
	s_addc_u32 s17, s17, 0
	s_add_u32 s50, s18, 0x100
	s_addc_u32 s51, s19, 0
	s_mov_b32 s52, -2
.LBB0_721:
	s_add_u32 s18, s16, 0xfff00080
	s_addc_u32 s19, s17, -1
	s_add_i32 s53, 0, 0x10000
	s_cmp_eq_u32 s52, 60
	s_cselect_b32 s23, s7, s19
	s_cselect_b32 s22, s48, s18
	v_add_u32_e32 v140, s53, v143
	s_cselect_b32 s19, s5, s51
	s_cselect_b32 s18, s49, s50
	s_add_i32 s56, 0, 0x14000
	ds_read_b128 v[146:149], v140
	ds_read_b128 v[150:153], v140 offset:1024
	ds_read_b128 v[154:157], v140 offset:2048
	ds_read_b128 v[158:161], v140 offset:3072
	v_add_u32_e32 v140, s56, v143
	ds_read_b128 v[162:165], v140
	ds_read_b128 v[166:169], v140 offset:1024
	ds_read_b128 v[170:173], v140 offset:2048
	ds_read_b128 v[178:181], v140 offset:3072
	v_lshl_add_u64 v[140:141], s[16:17], 0, v[136:137]
	s_add_i32 m0, s31, 0xc000
	ds_read_b128 v[190:193], v145
	ds_read_b128 v[194:197], v145 offset:1024
	ds_read_b128 v[198:201], v145 offset:2048
	ds_read_b128 v[202:205], v145 offset:3072
	ds_read_b128 v[206:209], v145 offset:4096
	ds_read_b128 v[228:231], v145 offset:5120
	ds_read_b128 v[232:235], v145 offset:6144
	ds_read_b128 v[236:239], v145 offset:7168
	global_load_lds_dwordx4 v[140:141], off
	v_lshl_add_u64 v[140:141], s[16:17], 0, v[138:139]
	s_add_i32 m0, s31, 0xe000
	s_nop 0
	global_load_lds_dwordx4 v[140:141], off
	s_waitcnt vmcnt(8)
	s_waitcnt lgkmcnt(0)
	s_cmp_eq_u32 s52, -2
	s_cbranch_scc1 .Lz0_2_0
	s_setprio 1
	s_barrier
	v_mfma_f32_16x16x32_bf16 v[126:129], v[146:149], v[190:193], v[126:129]
	v_mfma_f32_16x16x32_bf16 v[126:129], v[150:153], v[194:197], v[126:129]
	v_mfma_f32_16x16x32_bf16 v[110:113], v[150:153], v[202:205], v[110:113]
	v_mfma_f32_16x16x32_bf16 v[110:113], v[146:149], v[198:201], v[110:113]
	v_mfma_f32_16x16x32_bf16 v[94:97], v[146:149], v[206:209], v[94:97]
	v_mfma_f32_16x16x32_bf16 v[94:97], v[150:153], v[228:231], v[94:97]
	v_mfma_f32_16x16x32_bf16 v[78:81], v[150:153], v[236:239], v[78:81]
	v_mfma_f32_16x16x32_bf16 v[78:81], v[146:149], v[232:235], v[78:81]
	v_mfma_f32_16x16x32_bf16 v[70:73], v[154:157], v[232:235], v[70:73]
	v_mfma_f32_16x16x32_bf16 v[70:73], v[158:161], v[236:239], v[70:73]
	v_mfma_f32_16x16x32_bf16 v[86:89], v[158:161], v[228:231], v[86:89]
	v_mfma_f32_16x16x32_bf16 v[86:89], v[154:157], v[206:209], v[86:89]
	v_mfma_f32_16x16x32_bf16 v[102:105], v[154:157], v[198:201], v[102:105]
	v_mfma_f32_16x16x32_bf16 v[102:105], v[158:161], v[202:205], v[102:105]
	v_mfma_f32_16x16x32_bf16 v[118:121], v[158:161], v[194:197], v[118:121]
	v_mfma_f32_16x16x32_bf16 v[118:121], v[154:157], v[190:193], v[118:121]
	v_mfma_f32_16x16x32_bf16 v[122:125], v[162:165], v[190:193], v[122:125]
	v_mfma_f32_16x16x32_bf16 v[122:125], v[166:169], v[194:197], v[122:125]
	v_mfma_f32_16x16x32_bf16 v[106:109], v[166:169], v[202:205], v[106:109]
	v_mfma_f32_16x16x32_bf16 v[106:109], v[162:165], v[198:201], v[106:109]
	v_mfma_f32_16x16x32_bf16 v[90:93], v[162:165], v[206:209], v[90:93]
	v_mfma_f32_16x16x32_bf16 v[90:93], v[166:169], v[228:231], v[90:93]
	v_mfma_f32_16x16x32_bf16 v[74:77], v[166:169], v[236:239], v[74:77]
	v_mfma_f32_16x16x32_bf16 v[74:77], v[162:165], v[232:235], v[74:77]
	v_mfma_f32_16x16x32_bf16 v[66:69], v[170:173], v[232:235], v[66:69]
	v_mfma_f32_16x16x32_bf16 v[66:69], v[178:181], v[236:239], v[66:69]
	v_mfma_f32_16x16x32_bf16 v[82:85], v[178:181], v[228:231], v[82:85]
	v_mfma_f32_16x16x32_bf16 v[82:85], v[170:173], v[206:209], v[82:85]
	v_mfma_f32_16x16x32_bf16 v[98:101], v[170:173], v[198:201], v[98:101]
	v_mfma_f32_16x16x32_bf16 v[98:101], v[178:181], v[202:205], v[98:101]
	v_mfma_f32_16x16x32_bf16 v[114:117], v[178:181], v[194:197], v[114:117]
	v_mfma_f32_16x16x32_bf16 v[114:117], v[170:173], v[190:193], v[114:117]
	s_barrier
	s_setprio 0
.Lz0_2_0_ret:
	s_add_i32 s53, s53, s26
	v_lshl_add_u64 v[140:141], s[18:19], 0, v[0:1]
	s_mov_b32 m0, s53
	ds_read_b128 v[190:193], v145 offset:16384
	ds_read_b128 v[194:197], v145 offset:17408
	ds_read_b128 v[198:201], v145 offset:18432
	ds_read_b128 v[202:205], v145 offset:19456
	ds_read_b128 v[206:209], v145 offset:20480
	ds_read_b128 v[228:231], v145 offset:21504
	ds_read_b128 v[232:235], v145 offset:22528
	ds_read_b128 v[236:239], v145 offset:23552
	global_load_lds_dwordx4 v[140:141], off
	s_add_i32 m0, s53, 0x2000
	s_add_u32 s54, s18, 0x100000
	v_lshl_add_u64 v[186:187], s[18:19], 0, v[130:131]
	s_addc_u32 s55, s19, 0
	s_add_i32 s53, s56, s26
	global_load_lds_dwordx4 v[186:187], off
	v_lshl_add_u64 v[188:189], s[54:55], 0, v[0:1]
	s_mov_b32 m0, s53
	v_lshl_add_u64 v[210:211], s[22:23], 0, v[132:133]
	global_load_lds_dwordx4 v[188:189], off
	v_lshl_add_u64 v[188:189], s[54:55], 0, v[130:131]
	s_add_i32 m0, s53, 0x2000
	s_nop 0
	global_load_lds_dwordx4 v[188:189], off
	v_lshl_add_u64 v[188:189], s[22:23], 0, v[134:135]
	s_mov_b32 m0, s31
	s_nop 0
	global_load_lds_dwordx4 v[188:189], off
	s_mov_b32 m0, s40
	s_nop 0
	global_load_lds_dwordx4 v[210:211], off
	s_waitcnt vmcnt(8)
	s_waitcnt lgkmcnt(0)
	s_cmp_eq_u32 s52, -2
	s_cbranch_scc1 .Lz0_2_1
	s_setprio 1
	s_barrier
	v_mfma_f32_16x16x32_bf16 v[62:65], v[146:149], v[190:193], v[62:65]
	v_mfma_f32_16x16x32_bf16 v[62:65], v[150:153], v[194:197], v[62:65]
	v_mfma_f32_16x16x32_bf16 v[46:49], v[150:153], v[202:205], v[46:49]
	v_mfma_f32_16x16x32_bf16 v[46:49], v[146:149], v[198:201], v[46:49]
	v_mfma_f32_16x16x32_bf16 v[30:33], v[146:149], v[206:209], v[30:33]
	v_mfma_f32_16x16x32_bf16 v[30:33], v[150:153], v[228:231], v[30:33]
	v_mfma_f32_16x16x32_bf16 v[14:17], v[150:153], v[236:239], v[14:17]
	v_mfma_f32_16x16x32_bf16 v[14:17], v[146:149], v[232:235], v[14:17]
	v_mfma_f32_16x16x32_bf16 v[6:9], v[154:157], v[232:235], v[6:9]
	v_mfma_f32_16x16x32_bf16 v[6:9], v[158:161], v[236:239], v[6:9]
	v_mfma_f32_16x16x32_bf16 v[22:25], v[158:161], v[228:231], v[22:25]
	v_mfma_f32_16x16x32_bf16 v[22:25], v[154:157], v[206:209], v[22:25]
	v_mfma_f32_16x16x32_bf16 v[38:41], v[154:157], v[198:201], v[38:41]
	v_mfma_f32_16x16x32_bf16 v[38:41], v[158:161], v[202:205], v[38:41]
	v_mfma_f32_16x16x32_bf16 v[54:57], v[158:161], v[194:197], v[54:57]
	v_mfma_f32_16x16x32_bf16 v[54:57], v[154:157], v[190:193], v[54:57]
	v_mfma_f32_16x16x32_bf16 v[58:61], v[162:165], v[190:193], v[58:61]
	v_mfma_f32_16x16x32_bf16 v[58:61], v[166:169], v[194:197], v[58:61]
	v_mfma_f32_16x16x32_bf16 v[42:45], v[166:169], v[202:205], v[42:45]
	v_mfma_f32_16x16x32_bf16 v[42:45], v[162:165], v[198:201], v[42:45]
	v_mfma_f32_16x16x32_bf16 v[26:29], v[162:165], v[206:209], v[26:29]
	v_mfma_f32_16x16x32_bf16 v[26:29], v[166:169], v[228:231], v[26:29]
	v_mfma_f32_16x16x32_bf16 v[10:13], v[166:169], v[236:239], v[10:13]
	v_mfma_f32_16x16x32_bf16 v[10:13], v[162:165], v[232:235], v[10:13]
	v_mfma_f32_16x16x32_bf16 v[2:5], v[170:173], v[232:235], v[2:5]
	v_mfma_f32_16x16x32_bf16 v[2:5], v[178:181], v[236:239], v[2:5]
	v_mfma_f32_16x16x32_bf16 v[18:21], v[178:181], v[228:231], v[18:21]
	v_mfma_f32_16x16x32_bf16 v[18:21], v[170:173], v[206:209], v[18:21]
	v_mfma_f32_16x16x32_bf16 v[34:37], v[170:173], v[198:201], v[34:37]
	v_mfma_f32_16x16x32_bf16 v[34:37], v[178:181], v[202:205], v[34:37]
	v_mfma_f32_16x16x32_bf16 v[50:53], v[178:181], v[194:197], v[50:53]
	v_mfma_f32_16x16x32_bf16 v[50:53], v[170:173], v[190:193], v[50:53]
	s_barrier
	s_setprio 0
.Lz0_2_1_ret:
	s_add_i32 s53, 0, 0x18000
	s_add_i32 s54, 0, 0x1c000
	v_add_u32_e32 v158, s53, v143
	v_add_u32_e32 v175, s54, v143
	ds_read_b128 v[146:149], v158
	ds_read_b128 v[150:153], v158 offset:1024
	ds_read_b128 v[154:157], v158 offset:2048
	ds_read_b128 v[158:161], v158 offset:3072
	ds_read_b128 v[162:165], v175
	ds_read_b128 v[166:169], v175 offset:1024
	ds_read_b128 v[170:173], v175 offset:2048
	ds_read_b128 v[178:181], v175 offset:3072
	s_add_u32 s22, s22, 0x100000
	s_addc_u32 s23, s23, 0
	s_mov_b32 m0, s41
	v_lshl_add_u64 v[226:227], s[22:23], 0, v[134:135]
	ds_read_b128 v[190:193], v145 offset:32768
	ds_read_b128 v[194:197], v145 offset:33792
	ds_read_b128 v[198:201], v145 offset:34816
	ds_read_b128 v[202:205], v145 offset:35840
	ds_read_b128 v[206:209], v145 offset:36864
	ds_read_b128 v[228:231], v145 offset:37888
	ds_read_b128 v[232:235], v145 offset:38912
	ds_read_b128 v[236:239], v145 offset:39936
	global_load_lds_dwordx4 v[226:227], off
	v_lshl_add_u64 v[226:227], s[22:23], 0, v[132:133]
	s_mov_b32 m0, s42
	s_nop 0
	global_load_lds_dwordx4 v[226:227], off
	s_waitcnt vmcnt(8)
	s_waitcnt lgkmcnt(0)
	s_setprio 1
	s_barrier
	v_mfma_f32_16x16x32_bf16 v[126:129], v[146:149], v[190:193], v[126:129]
	v_mfma_f32_16x16x32_bf16 v[126:129], v[150:153], v[194:197], v[126:129]
	v_mfma_f32_16x16x32_bf16 v[110:113], v[150:153], v[202:205], v[110:113]
	v_mfma_f32_16x16x32_bf16 v[110:113], v[146:149], v[198:201], v[110:113]
	v_mfma_f32_16x16x32_bf16 v[94:97], v[146:149], v[206:209], v[94:97]
	v_mfma_f32_16x16x32_bf16 v[94:97], v[150:153], v[228:231], v[94:97]
	v_mfma_f32_16x16x32_bf16 v[78:81], v[150:153], v[236:239], v[78:81]
	v_mfma_f32_16x16x32_bf16 v[78:81], v[146:149], v[232:235], v[78:81]
	v_mfma_f32_16x16x32_bf16 v[70:73], v[154:157], v[232:235], v[70:73]
	v_mfma_f32_16x16x32_bf16 v[70:73], v[158:161], v[236:239], v[70:73]
	v_mfma_f32_16x16x32_bf16 v[86:89], v[158:161], v[228:231], v[86:89]
	v_mfma_f32_16x16x32_bf16 v[86:89], v[154:157], v[206:209], v[86:89]
	v_mfma_f32_16x16x32_bf16 v[102:105], v[154:157], v[198:201], v[102:105]
	v_mfma_f32_16x16x32_bf16 v[102:105], v[158:161], v[202:205], v[102:105]
	v_mfma_f32_16x16x32_bf16 v[118:121], v[158:161], v[194:197], v[118:121]
	v_mfma_f32_16x16x32_bf16 v[118:121], v[154:157], v[190:193], v[118:121]
	v_mfma_f32_16x16x32_bf16 v[122:125], v[162:165], v[190:193], v[122:125]
	v_mfma_f32_16x16x32_bf16 v[122:125], v[166:169], v[194:197], v[122:125]
	v_mfma_f32_16x16x32_bf16 v[106:109], v[166:169], v[202:205], v[106:109]
	v_mfma_f32_16x16x32_bf16 v[106:109], v[162:165], v[198:201], v[106:109]
	v_mfma_f32_16x16x32_bf16 v[90:93], v[162:165], v[206:209], v[90:93]
	v_mfma_f32_16x16x32_bf16 v[90:93], v[166:169], v[228:231], v[90:93]
	v_mfma_f32_16x16x32_bf16 v[74:77], v[166:169], v[236:239], v[74:77]
	v_mfma_f32_16x16x32_bf16 v[74:77], v[162:165], v[232:235], v[74:77]
	v_mfma_f32_16x16x32_bf16 v[66:69], v[170:173], v[232:235], v[66:69]
	v_mfma_f32_16x16x32_bf16 v[66:69], v[178:181], v[236:239], v[66:69]
	v_mfma_f32_16x16x32_bf16 v[82:85], v[178:181], v[228:231], v[82:85]
	v_mfma_f32_16x16x32_bf16 v[82:85], v[170:173], v[206:209], v[82:85]
	v_mfma_f32_16x16x32_bf16 v[98:101], v[170:173], v[198:201], v[98:101]
	v_mfma_f32_16x16x32_bf16 v[98:101], v[178:181], v[202:205], v[98:101]
	v_mfma_f32_16x16x32_bf16 v[114:117], v[178:181], v[194:197], v[114:117]
	v_mfma_f32_16x16x32_bf16 v[114:117], v[170:173], v[190:193], v[114:117]
	s_barrier
	s_setprio 0
	s_add_i32 s22, s53, s26
	v_lshl_add_u64 v[140:141], v[140:141], 0, s[34:35]
	s_mov_b32 m0, s22
	ds_read_b128 v[190:193], v145 offset:49152
	ds_read_b128 v[194:197], v145 offset:50176
	ds_read_b128 v[198:201], v145 offset:51200
	ds_read_b128 v[202:205], v145 offset:52224
	ds_read_b128 v[206:209], v145 offset:53248
	ds_read_b128 v[228:231], v145 offset:54272
	ds_read_b128 v[232:235], v145 offset:55296
	ds_read_b128 v[236:239], v145 offset:56320
	global_load_lds_dwordx4 v[140:141], off
	s_add_i32 m0, s22, 0x2000
	s_add_u32 s18, s18, 0x100080
	v_lshl_add_u64 v[140:141], v[186:187], 0, s[34:35]
	s_addc_u32 s19, s19, 0
	s_add_i32 s22, s54, s26
	global_load_lds_dwordx4 v[140:141], off
	v_lshl_add_u64 v[140:141], s[18:19], 0, v[0:1]
	s_mov_b32 m0, s22
	s_nop 0
	global_load_lds_dwordx4 v[140:141], off
	v_lshl_add_u64 v[140:141], s[18:19], 0, v[130:131]
	s_add_i32 m0, s22, 0x2000
	s_nop 0
	global_load_lds_dwordx4 v[140:141], off
	v_lshl_add_u64 v[140:141], v[188:189], 0, s[34:35]
	s_mov_b32 m0, s43
	s_nop 0
	global_load_lds_dwordx4 v[140:141], off
	v_lshl_add_u64 v[140:141], v[210:211], 0, s[34:35]
	s_mov_b32 m0, s44
	s_nop 0
	global_load_lds_dwordx4 v[140:141], off
	s_waitcnt vmcnt(8)
	s_waitcnt lgkmcnt(0)
	s_setprio 1
	s_barrier
	v_mfma_f32_16x16x32_bf16 v[62:65], v[146:149], v[190:193], v[62:65]
	v_mfma_f32_16x16x32_bf16 v[62:65], v[150:153], v[194:197], v[62:65]
	v_mfma_f32_16x16x32_bf16 v[46:49], v[150:153], v[202:205], v[46:49]
	v_mfma_f32_16x16x32_bf16 v[46:49], v[146:149], v[198:201], v[46:49]
	v_mfma_f32_16x16x32_bf16 v[30:33], v[146:149], v[206:209], v[30:33]
	v_mfma_f32_16x16x32_bf16 v[30:33], v[150:153], v[228:231], v[30:33]
	v_mfma_f32_16x16x32_bf16 v[14:17], v[150:153], v[236:239], v[14:17]
	v_mfma_f32_16x16x32_bf16 v[14:17], v[146:149], v[232:235], v[14:17]
	v_mfma_f32_16x16x32_bf16 v[6:9], v[154:157], v[232:235], v[6:9]
	v_mfma_f32_16x16x32_bf16 v[6:9], v[158:161], v[236:239], v[6:9]
	v_mfma_f32_16x16x32_bf16 v[22:25], v[158:161], v[228:231], v[22:25]
	v_mfma_f32_16x16x32_bf16 v[22:25], v[154:157], v[206:209], v[22:25]
	v_mfma_f32_16x16x32_bf16 v[38:41], v[154:157], v[198:201], v[38:41]
	v_mfma_f32_16x16x32_bf16 v[38:41], v[158:161], v[202:205], v[38:41]
	v_mfma_f32_16x16x32_bf16 v[54:57], v[158:161], v[194:197], v[54:57]
	v_mfma_f32_16x16x32_bf16 v[54:57], v[154:157], v[190:193], v[54:57]
	v_mfma_f32_16x16x32_bf16 v[58:61], v[162:165], v[190:193], v[58:61]
	v_mfma_f32_16x16x32_bf16 v[58:61], v[166:169], v[194:197], v[58:61]
	v_mfma_f32_16x16x32_bf16 v[42:45], v[166:169], v[202:205], v[42:45]
	v_mfma_f32_16x16x32_bf16 v[42:45], v[162:165], v[198:201], v[42:45]
	v_mfma_f32_16x16x32_bf16 v[26:29], v[162:165], v[206:209], v[26:29]
	v_mfma_f32_16x16x32_bf16 v[26:29], v[166:169], v[228:231], v[26:29]
	v_mfma_f32_16x16x32_bf16 v[10:13], v[166:169], v[236:239], v[10:13]
	v_mfma_f32_16x16x32_bf16 v[10:13], v[162:165], v[232:235], v[10:13]
	v_mfma_f32_16x16x32_bf16 v[2:5], v[170:173], v[232:235], v[2:5]
	v_mfma_f32_16x16x32_bf16 v[2:5], v[178:181], v[236:239], v[2:5]
	v_mfma_f32_16x16x32_bf16 v[18:21], v[178:181], v[228:231], v[18:21]
	v_mfma_f32_16x16x32_bf16 v[18:21], v[170:173], v[206:209], v[18:21]
	v_mfma_f32_16x16x32_bf16 v[34:37], v[170:173], v[198:201], v[34:37]
	v_mfma_f32_16x16x32_bf16 v[34:37], v[178:181], v[202:205], v[34:37]
	v_mfma_f32_16x16x32_bf16 v[50:53], v[178:181], v[194:197], v[50:53]
	v_mfma_f32_16x16x32_bf16 v[50:53], v[170:173], v[190:193], v[50:53]
	s_barrier
	s_setprio 0
	s_add_i32 s52, s52, 2
	s_add_u32 s16, s16, 0x100
	s_addc_u32 s17, s17, 0
	s_add_u32 s50, s50, 0x100
	s_addc_u32 s51, s51, 0
	s_cmp_gt_u32 s52, 61
	s_cbranch_scc0 .LBB0_721
	s_and_b64 vcc, exec, s[2:3]
	s_cbranch_vccz .LBB0_724
	s_barrier

.Lz0_2_0:
	s_setprio 1
	s_barrier
	v_mfma_f32_16x16x32_bf16 v[126:129], v[146:149], v[190:193], 0
	v_mfma_f32_16x16x32_bf16 v[126:129], v[150:153], v[194:197], v[126:129]
	v_mfma_f32_16x16x32_bf16 v[110:113], v[150:153], v[202:205], 0
	v_mfma_f32_16x16x32_bf16 v[110:113], v[146:149], v[198:201], v[110:113]
	v_mfma_f32_16x16x32_bf16 v[94:97], v[146:149], v[206:209], 0
	v_mfma_f32_16x16x32_bf16 v[94:97], v[150:153], v[228:231], v[94:97]
	v_mfma_f32_16x16x32_bf16 v[78:81], v[150:153], v[236:239], 0
	v_mfma_f32_16x16x32_bf16 v[78:81], v[146:149], v[232:235], v[78:81]
	v_mfma_f32_16x16x32_bf16 v[70:73], v[154:157], v[232:235], 0
	v_mfma_f32_16x16x32_bf16 v[70:73], v[158:161], v[236:239], v[70:73]
	v_mfma_f32_16x16x32_bf16 v[86:89], v[158:161], v[228:231], 0
	v_mfma_f32_16x16x32_bf16 v[86:89], v[154:157], v[206:209], v[86:89]
	v_mfma_f32_16x16x32_bf16 v[102:105], v[154:157], v[198:201], 0
	v_mfma_f32_16x16x32_bf16 v[102:105], v[158:161], v[202:205], v[102:105]
	v_mfma_f32_16x16x32_bf16 v[118:121], v[158:161], v[194:197], 0
	v_mfma_f32_16x16x32_bf16 v[118:121], v[154:157], v[190:193], v[118:121]
	v_mfma_f32_16x16x32_bf16 v[122:125], v[162:165], v[190:193], 0
	v_mfma_f32_16x16x32_bf16 v[122:125], v[166:169], v[194:197], v[122:125]
	v_mfma_f32_16x16x32_bf16 v[106:109], v[166:169], v[202:205], 0
	v_mfma_f32_16x16x32_bf16 v[106:109], v[162:165], v[198:201], v[106:109]
	v_mfma_f32_16x16x32_bf16 v[90:93], v[162:165], v[206:209], 0
	v_mfma_f32_16x16x32_bf16 v[90:93], v[166:169], v[228:231], v[90:93]
	v_mfma_f32_16x16x32_bf16 v[74:77], v[166:169], v[236:239], 0
	v_mfma_f32_16x16x32_bf16 v[74:77], v[162:165], v[232:235], v[74:77]
	v_mfma_f32_16x16x32_bf16 v[66:69], v[170:173], v[232:235], 0
	v_mfma_f32_16x16x32_bf16 v[66:69], v[178:181], v[236:239], v[66:69]
	v_mfma_f32_16x16x32_bf16 v[82:85], v[178:181], v[228:231], 0
	v_mfma_f32_16x16x32_bf16 v[82:85], v[170:173], v[206:209], v[82:85]
	v_mfma_f32_16x16x32_bf16 v[98:101], v[170:173], v[198:201], 0
	v_mfma_f32_16x16x32_bf16 v[98:101], v[178:181], v[202:205], v[98:101]
	v_mfma_f32_16x16x32_bf16 v[114:117], v[178:181], v[194:197], 0
	v_mfma_f32_16x16x32_bf16 v[114:117], v[170:173], v[190:193], v[114:117]
	s_barrier
	s_setprio 0
	s_branch .Lz0_2_0_ret
.Lz0_2_1:
	s_setprio 1
	s_barrier
	v_mfma_f32_16x16x32_bf16 v[62:65], v[146:149], v[190:193], 0
	v_mfma_f32_16x16x32_bf16 v[62:65], v[150:153], v[194:197], v[62:65]
	v_mfma_f32_16x16x32_bf16 v[46:49], v[150:153], v[202:205], 0
	v_mfma_f32_16x16x32_bf16 v[46:49], v[146:149], v[198:201], v[46:49]
	v_mfma_f32_16x16x32_bf16 v[30:33], v[146:149], v[206:209], 0
	v_mfma_f32_16x16x32_bf16 v[30:33], v[150:153], v[228:231], v[30:33]
	v_mfma_f32_16x16x32_bf16 v[14:17], v[150:153], v[236:239], 0
	v_mfma_f32_16x16x32_bf16 v[14:17], v[146:149], v[232:235], v[14:17]
	v_mfma_f32_16x16x32_bf16 v[6:9], v[154:157], v[232:235], 0
	v_mfma_f32_16x16x32_bf16 v[6:9], v[158:161], v[236:239], v[6:9]
	v_mfma_f32_16x16x32_bf16 v[22:25], v[158:161], v[228:231], 0
	v_mfma_f32_16x16x32_bf16 v[22:25], v[154:157], v[206:209], v[22:25]
	v_mfma_f32_16x16x32_bf16 v[38:41], v[154:157], v[198:201], 0
	v_mfma_f32_16x16x32_bf16 v[38:41], v[158:161], v[202:205], v[38:41]
	v_mfma_f32_16x16x32_bf16 v[54:57], v[158:161], v[194:197], 0
	v_mfma_f32_16x16x32_bf16 v[54:57], v[154:157], v[190:193], v[54:57]
	v_mfma_f32_16x16x32_bf16 v[58:61], v[162:165], v[190:193], 0
	v_mfma_f32_16x16x32_bf16 v[58:61], v[166:169], v[194:197], v[58:61]
	v_mfma_f32_16x16x32_bf16 v[42:45], v[166:169], v[202:205], 0
	v_mfma_f32_16x16x32_bf16 v[42:45], v[162:165], v[198:201], v[42:45]
	v_mfma_f32_16x16x32_bf16 v[26:29], v[162:165], v[206:209], 0
	v_mfma_f32_16x16x32_bf16 v[26:29], v[166:169], v[228:231], v[26:29]
	v_mfma_f32_16x16x32_bf16 v[10:13], v[166:169], v[236:239], 0
	v_mfma_f32_16x16x32_bf16 v[10:13], v[162:165], v[232:235], v[10:13]
	v_mfma_f32_16x16x32_bf16 v[2:5], v[170:173], v[232:235], 0
	v_mfma_f32_16x16x32_bf16 v[2:5], v[178:181], v[236:239], v[2:5]
	v_mfma_f32_16x16x32_bf16 v[18:21], v[178:181], v[228:231], 0
	v_mfma_f32_16x16x32_bf16 v[18:21], v[170:173], v[206:209], v[18:21]
	v_mfma_f32_16x16x32_bf16 v[34:37], v[170:173], v[198:201], 0
	v_mfma_f32_16x16x32_bf16 v[34:37], v[178:181], v[202:205], v[34:37]
	v_mfma_f32_16x16x32_bf16 v[50:53], v[178:181], v[194:197], 0
	v_mfma_f32_16x16x32_bf16 v[50:53], v[170:173], v[190:193], v[50:53]
	s_barrier
	s_setprio 0
	s_branch .Lz0_2_1_ret

.LBB0_804:
	s_add_u32 s46, s16, 0x100
	s_addc_u32 s47, s17, 0
	s_mov_b32 s48, -2
.LBB0_805:
	s_add_u32 s16, s14, 0x100
	s_addc_u32 s17, s15, 0
	s_add_i32 s49, 0, 0x10000
	s_cmpk_eq_i32 s48, 0xa8
	s_cselect_b32 s23, s5, s17
	s_cselect_b32 s22, s4, s16
	v_add_u32_e32 v140, s49, v143
	s_cselect_b32 s19, s9, s47
	s_cselect_b32 s18, s8, s46
	s_add_i32 s50, 0, 0x14000
	ds_read_b128 v[146:149], v140
	ds_read_b128 v[150:153], v140 offset:1024
	ds_read_b128 v[154:157], v140 offset:2048
	ds_read_b128 v[158:161], v140 offset:3072
	v_add_u32_e32 v140, s50, v143
	ds_read_b128 v[162:165], v140
	ds_read_b128 v[166:169], v140 offset:1024
	ds_read_b128 v[170:173], v140 offset:2048
	ds_read_b128 v[178:181], v140 offset:3072
	v_lshl_add_u64 v[140:141], s[14:15], 0, v[136:137]
	s_add_i32 m0, s31, 0xc000
	ds_read_b128 v[190:193], v145
	ds_read_b128 v[194:197], v145 offset:1024
	ds_read_b128 v[198:201], v145 offset:2048
	ds_read_b128 v[202:205], v145 offset:3072
	ds_read_b128 v[206:209], v145 offset:4096
	ds_read_b128 v[228:231], v145 offset:5120
	ds_read_b128 v[232:235], v145 offset:6144
	ds_read_b128 v[236:239], v145 offset:7168
	global_load_lds_dwordx4 v[140:141], off
	v_lshl_add_u64 v[140:141], s[14:15], 0, v[138:139]
	s_add_i32 m0, s31, 0xe000
	s_nop 0
	global_load_lds_dwordx4 v[140:141], off
	s_waitcnt vmcnt(8)
	s_waitcnt lgkmcnt(0)
	s_cmp_eq_u32 s48, -2
	s_cbranch_scc1 .Lz0_3_0
	s_setprio 1
	s_barrier
	v_mfma_f32_16x16x32_bf16 v[126:129], v[146:149], v[190:193], v[126:129]
	v_mfma_f32_16x16x32_bf16 v[126:129], v[150:153], v[194:197], v[126:129]
	v_mfma_f32_16x16x32_bf16 v[118:121], v[150:153], v[202:205], v[118:121]
	v_mfma_f32_16x16x32_bf16 v[118:121], v[146:149], v[198:201], v[118:121]
	v_mfma_f32_16x16x32_bf16 v[102:105], v[146:149], v[206:209], v[102:105]
	v_mfma_f32_16x16x32_bf16 v[102:105], v[150:153], v[228:231], v[102:105]
	v_mfma_f32_16x16x32_bf16 v[86:89], v[150:153], v[236:239], v[86:89]
	v_mfma_f32_16x16x32_bf16 v[86:89], v[146:149], v[232:235], v[86:89]
	v_mfma_f32_16x16x32_bf16 v[78:81], v[154:157], v[232:235], v[78:81]
	v_mfma_f32_16x16x32_bf16 v[78:81], v[158:161], v[236:239], v[78:81]
	v_mfma_f32_16x16x32_bf16 v[94:97], v[158:161], v[228:231], v[94:97]
	v_mfma_f32_16x16x32_bf16 v[94:97], v[154:157], v[206:209], v[94:97]
	v_mfma_f32_16x16x32_bf16 v[110:113], v[154:157], v[198:201], v[110:113]
	v_mfma_f32_16x16x32_bf16 v[110:113], v[158:161], v[202:205], v[110:113]
	v_mfma_f32_16x16x32_bf16 v[122:125], v[158:161], v[194:197], v[122:125]
	v_mfma_f32_16x16x32_bf16 v[122:125], v[154:157], v[190:193], v[122:125]
	v_mfma_f32_16x16x32_bf16 v[114:117], v[162:165], v[190:193], v[114:117]
	v_mfma_f32_16x16x32_bf16 v[114:117], v[166:169], v[194:197], v[114:117]
	v_mfma_f32_16x16x32_bf16 v[98:101], v[166:169], v[202:205], v[98:101]
	v_mfma_f32_16x16x32_bf16 v[98:101], v[162:165], v[198:201], v[98:101]
	v_mfma_f32_16x16x32_bf16 v[82:85], v[162:165], v[206:209], v[82:85]
	v_mfma_f32_16x16x32_bf16 v[82:85], v[166:169], v[228:231], v[82:85]
	v_mfma_f32_16x16x32_bf16 v[70:73], v[166:169], v[236:239], v[70:73]
	v_mfma_f32_16x16x32_bf16 v[70:73], v[162:165], v[232:235], v[70:73]
	v_mfma_f32_16x16x32_bf16 v[66:69], v[170:173], v[232:235], v[66:69]
	v_mfma_f32_16x16x32_bf16 v[66:69], v[178:181], v[236:239], v[66:69]
	v_mfma_f32_16x16x32_bf16 v[74:77], v[178:181], v[228:231], v[74:77]
	v_mfma_f32_16x16x32_bf16 v[74:77], v[170:173], v[206:209], v[74:77]
	v_mfma_f32_16x16x32_bf16 v[90:93], v[170:173], v[198:201], v[90:93]
	v_mfma_f32_16x16x32_bf16 v[90:93], v[178:181], v[202:205], v[90:93]
	v_mfma_f32_16x16x32_bf16 v[106:109], v[178:181], v[194:197], v[106:109]
	v_mfma_f32_16x16x32_bf16 v[106:109], v[170:173], v[190:193], v[106:109]
	s_barrier
	s_setprio 0
.Lz0_3_0_ret:
	s_add_i32 s14, s49, s26
	v_lshl_add_u64 v[140:141], s[18:19], 0, v[0:1]
	s_mov_b32 m0, s14
	ds_read_b128 v[190:193], v145 offset:16384
	ds_read_b128 v[194:197], v145 offset:17408
	ds_read_b128 v[198:201], v145 offset:18432
	ds_read_b128 v[202:205], v145 offset:19456
	ds_read_b128 v[206:209], v145 offset:20480
	ds_read_b128 v[228:231], v145 offset:21504
	ds_read_b128 v[232:235], v145 offset:22528
	ds_read_b128 v[236:239], v145 offset:23552
	global_load_lds_dwordx4 v[140:141], off
	s_add_i32 m0, s14, 0x2000
	s_add_u32 s14, s18, 0x2b0000
	v_lshl_add_u64 v[186:187], s[18:19], 0, v[130:131]
	s_addc_u32 s15, s19, 0
	s_add_i32 s49, s50, s26
	global_load_lds_dwordx4 v[186:187], off
	v_lshl_add_u64 v[188:189], s[14:15], 0, v[0:1]
	s_mov_b32 m0, s49
	v_lshl_add_u64 v[210:211], s[22:23], 0, v[132:133]
	global_load_lds_dwordx4 v[188:189], off
	v_lshl_add_u64 v[188:189], s[14:15], 0, v[130:131]
	s_add_i32 m0, s49, 0x2000
	s_nop 0
	global_load_lds_dwordx4 v[188:189], off
	v_lshl_add_u64 v[188:189], s[22:23], 0, v[134:135]
	s_mov_b32 m0, s31
	s_nop 0
	global_load_lds_dwordx4 v[188:189], off
	s_mov_b32 m0, s36
	s_nop 0
	global_load_lds_dwordx4 v[210:211], off
	s_waitcnt vmcnt(8)
	s_waitcnt lgkmcnt(0)
	s_cmp_eq_u32 s48, -2
	s_cbranch_scc1 .Lz0_3_1
	s_setprio 1
	s_barrier
	v_mfma_f32_16x16x32_bf16 v[62:65], v[146:149], v[190:193], v[62:65]
	v_mfma_f32_16x16x32_bf16 v[62:65], v[150:153], v[194:197], v[62:65]
	v_mfma_f32_16x16x32_bf16 v[54:57], v[150:153], v[202:205], v[54:57]
	v_mfma_f32_16x16x32_bf16 v[54:57], v[146:149], v[198:201], v[54:57]
	v_mfma_f32_16x16x32_bf16 v[38:41], v[146:149], v[206:209], v[38:41]
	v_mfma_f32_16x16x32_bf16 v[38:41], v[150:153], v[228:231], v[38:41]
	v_mfma_f32_16x16x32_bf16 v[22:25], v[150:153], v[236:239], v[22:25]
	v_mfma_f32_16x16x32_bf16 v[22:25], v[146:149], v[232:235], v[22:25]
	v_mfma_f32_16x16x32_bf16 v[14:17], v[154:157], v[232:235], v[14:17]
	v_mfma_f32_16x16x32_bf16 v[14:17], v[158:161], v[236:239], v[14:17]
	v_mfma_f32_16x16x32_bf16 v[30:33], v[158:161], v[228:231], v[30:33]
	v_mfma_f32_16x16x32_bf16 v[30:33], v[154:157], v[206:209], v[30:33]
	v_mfma_f32_16x16x32_bf16 v[46:49], v[154:157], v[198:201], v[46:49]
	v_mfma_f32_16x16x32_bf16 v[46:49], v[158:161], v[202:205], v[46:49]
	v_mfma_f32_16x16x32_bf16 v[58:61], v[158:161], v[194:197], v[58:61]
	v_mfma_f32_16x16x32_bf16 v[58:61], v[154:157], v[190:193], v[58:61]
	v_mfma_f32_16x16x32_bf16 v[50:53], v[162:165], v[190:193], v[50:53]
	v_mfma_f32_16x16x32_bf16 v[50:53], v[166:169], v[194:197], v[50:53]
	v_mfma_f32_16x16x32_bf16 v[34:37], v[166:169], v[202:205], v[34:37]
	v_mfma_f32_16x16x32_bf16 v[34:37], v[162:165], v[198:201], v[34:37]
	v_mfma_f32_16x16x32_bf16 v[18:21], v[162:165], v[206:209], v[18:21]
	v_mfma_f32_16x16x32_bf16 v[18:21], v[166:169], v[228:231], v[18:21]
	v_mfma_f32_16x16x32_bf16 v[6:9], v[166:169], v[236:239], v[6:9]
	v_mfma_f32_16x16x32_bf16 v[6:9], v[162:165], v[232:235], v[6:9]
	v_mfma_f32_16x16x32_bf16 v[2:5], v[170:173], v[232:235], v[2:5]
	v_mfma_f32_16x16x32_bf16 v[2:5], v[178:181], v[236:239], v[2:5]
	v_mfma_f32_16x16x32_bf16 v[10:13], v[178:181], v[228:231], v[10:13]
	v_mfma_f32_16x16x32_bf16 v[10:13], v[170:173], v[206:209], v[10:13]
	v_mfma_f32_16x16x32_bf16 v[26:29], v[170:173], v[198:201], v[26:29]
	v_mfma_f32_16x16x32_bf16 v[26:29], v[178:181], v[202:205], v[26:29]
	v_mfma_f32_16x16x32_bf16 v[42:45], v[178:181], v[194:197], v[42:45]
	v_mfma_f32_16x16x32_bf16 v[42:45], v[170:173], v[190:193], v[42:45]
	s_barrier
	s_setprio 0
.Lz0_3_1_ret:
	s_add_i32 s49, 0, 0x18000
	s_add_i32 s50, 0, 0x1c000
	v_add_u32_e32 v158, s49, v143
	v_add_u32_e32 v175, s50, v143
	ds_read_b128 v[146:149], v158
	ds_read_b128 v[150:153], v158 offset:1024
	ds_read_b128 v[154:157], v158 offset:2048
	ds_read_b128 v[158:161], v158 offset:3072
	ds_read_b128 v[162:165], v175
	ds_read_b128 v[166:169], v175 offset:1024
	ds_read_b128 v[170:173], v175 offset:2048
	ds_read_b128 v[178:181], v175 offset:3072
	s_add_u32 s14, s22, 0x2b0000
	s_addc_u32 s15, s23, 0
	s_mov_b32 m0, s37
	v_lshl_add_u64 v[226:227], s[14:15], 0, v[134:135]
	ds_read_b128 v[190:193], v145 offset:32768
	ds_read_b128 v[194:197], v145 offset:33792
	ds_read_b128 v[198:201], v145 offset:34816
	ds_read_b128 v[202:205], v145 offset:35840
	ds_read_b128 v[206:209], v145 offset:36864
	ds_read_b128 v[228:231], v145 offset:37888
	ds_read_b128 v[232:235], v145 offset:38912
	ds_read_b128 v[236:239], v145 offset:39936
	global_load_lds_dwordx4 v[226:227], off
	v_lshl_add_u64 v[226:227], s[14:15], 0, v[132:133]
	s_mov_b32 m0, s38
	s_nop 0
	global_load_lds_dwordx4 v[226:227], off
	s_waitcnt vmcnt(8)
	s_waitcnt lgkmcnt(0)
	s_setprio 1
	s_barrier
	v_mfma_f32_16x16x32_bf16 v[126:129], v[146:149], v[190:193], v[126:129]
	v_mfma_f32_16x16x32_bf16 v[126:129], v[150:153], v[194:197], v[126:129]
	v_mfma_f32_16x16x32_bf16 v[118:121], v[150:153], v[202:205], v[118:121]
	v_mfma_f32_16x16x32_bf16 v[118:121], v[146:149], v[198:201], v[118:121]
	v_mfma_f32_16x16x32_bf16 v[102:105], v[146:149], v[206:209], v[102:105]
	v_mfma_f32_16x16x32_bf16 v[102:105], v[150:153], v[228:231], v[102:105]
	v_mfma_f32_16x16x32_bf16 v[86:89], v[150:153], v[236:239], v[86:89]
	v_mfma_f32_16x16x32_bf16 v[86:89], v[146:149], v[232:235], v[86:89]
	v_mfma_f32_16x16x32_bf16 v[78:81], v[154:157], v[232:235], v[78:81]
	v_mfma_f32_16x16x32_bf16 v[78:81], v[158:161], v[236:239], v[78:81]
	v_mfma_f32_16x16x32_bf16 v[94:97], v[158:161], v[228:231], v[94:97]
	v_mfma_f32_16x16x32_bf16 v[94:97], v[154:157], v[206:209], v[94:97]
	v_mfma_f32_16x16x32_bf16 v[110:113], v[154:157], v[198:201], v[110:113]
	v_mfma_f32_16x16x32_bf16 v[110:113], v[158:161], v[202:205], v[110:113]
	v_mfma_f32_16x16x32_bf16 v[122:125], v[158:161], v[194:197], v[122:125]
	v_mfma_f32_16x16x32_bf16 v[122:125], v[154:157], v[190:193], v[122:125]
	v_mfma_f32_16x16x32_bf16 v[114:117], v[162:165], v[190:193], v[114:117]
	v_mfma_f32_16x16x32_bf16 v[114:117], v[166:169], v[194:197], v[114:117]
	v_mfma_f32_16x16x32_bf16 v[98:101], v[166:169], v[202:205], v[98:101]
	v_mfma_f32_16x16x32_bf16 v[98:101], v[162:165], v[198:201], v[98:101]
	v_mfma_f32_16x16x32_bf16 v[82:85], v[162:165], v[206:209], v[82:85]
	v_mfma_f32_16x16x32_bf16 v[82:85], v[166:169], v[228:231], v[82:85]
	v_mfma_f32_16x16x32_bf16 v[70:73], v[166:169], v[236:239], v[70:73]
	v_mfma_f32_16x16x32_bf16 v[70:73], v[162:165], v[232:235], v[70:73]
	v_mfma_f32_16x16x32_bf16 v[66:69], v[170:173], v[232:235], v[66:69]
	v_mfma_f32_16x16x32_bf16 v[66:69], v[178:181], v[236:239], v[66:69]
	v_mfma_f32_16x16x32_bf16 v[74:77], v[178:181], v[228:231], v[74:77]
	v_mfma_f32_16x16x32_bf16 v[74:77], v[170:173], v[206:209], v[74:77]
	v_mfma_f32_16x16x32_bf16 v[90:93], v[170:173], v[198:201], v[90:93]
	v_mfma_f32_16x16x32_bf16 v[90:93], v[178:181], v[202:205], v[90:93]
	v_mfma_f32_16x16x32_bf16 v[106:109], v[178:181], v[194:197], v[106:109]
	v_mfma_f32_16x16x32_bf16 v[106:109], v[170:173], v[190:193], v[106:109]
	s_barrier
	s_setprio 0
	s_add_i32 s14, s49, s26
	v_lshl_add_u64 v[140:141], v[140:141], 0, s[34:35]
	s_mov_b32 m0, s14
	ds_read_b128 v[190:193], v145 offset:49152
	ds_read_b128 v[194:197], v145 offset:50176
	ds_read_b128 v[198:201], v145 offset:51200
	ds_read_b128 v[202:205], v145 offset:52224
	ds_read_b128 v[206:209], v145 offset:53248
	ds_read_b128 v[228:231], v145 offset:54272
	ds_read_b128 v[232:235], v145 offset:55296
	ds_read_b128 v[236:239], v145 offset:56320
	global_load_lds_dwordx4 v[140:141], off
	s_add_i32 m0, s14, 0x2000
	s_add_u32 s14, s18, 0x2b0080
	v_lshl_add_u64 v[140:141], v[186:187], 0, s[34:35]
	s_addc_u32 s15, s19, 0
	s_add_i32 s18, s50, s26
	global_load_lds_dwordx4 v[140:141], off
	v_lshl_add_u64 v[140:141], s[14:15], 0, v[0:1]
	s_mov_b32 m0, s18
	s_nop 0
	global_load_lds_dwordx4 v[140:141], off
	v_lshl_add_u64 v[140:141], s[14:15], 0, v[130:131]
	s_add_i32 m0, s18, 0x2000
	s_nop 0
	global_load_lds_dwordx4 v[140:141], off
	v_lshl_add_u64 v[140:141], v[188:189], 0, s[34:35]
	s_mov_b32 m0, s39
	s_nop 0
	global_load_lds_dwordx4 v[140:141], off
	v_lshl_add_u64 v[140:141], v[210:211], 0, s[34:35]
	s_mov_b32 m0, s40
	s_nop 0
	global_load_lds_dwordx4 v[140:141], off
	s_waitcnt vmcnt(8)
	s_waitcnt lgkmcnt(0)
	s_setprio 1
	s_barrier
	v_mfma_f32_16x16x32_bf16 v[62:65], v[146:149], v[190:193], v[62:65]
	v_mfma_f32_16x16x32_bf16 v[62:65], v[150:153], v[194:197], v[62:65]
	v_mfma_f32_16x16x32_bf16 v[54:57], v[150:153], v[202:205], v[54:57]
	v_mfma_f32_16x16x32_bf16 v[54:57], v[146:149], v[198:201], v[54:57]
	v_mfma_f32_16x16x32_bf16 v[38:41], v[146:149], v[206:209], v[38:41]
	v_mfma_f32_16x16x32_bf16 v[38:41], v[150:153], v[228:231], v[38:41]
	v_mfma_f32_16x16x32_bf16 v[22:25], v[150:153], v[236:239], v[22:25]
	v_mfma_f32_16x16x32_bf16 v[22:25], v[146:149], v[232:235], v[22:25]
	v_mfma_f32_16x16x32_bf16 v[14:17], v[154:157], v[232:235], v[14:17]
	v_mfma_f32_16x16x32_bf16 v[14:17], v[158:161], v[236:239], v[14:17]
	v_mfma_f32_16x16x32_bf16 v[30:33], v[158:161], v[228:231], v[30:33]
	v_mfma_f32_16x16x32_bf16 v[30:33], v[154:157], v[206:209], v[30:33]
	v_mfma_f32_16x16x32_bf16 v[46:49], v[154:157], v[198:201], v[46:49]
	v_mfma_f32_16x16x32_bf16 v[46:49], v[158:161], v[202:205], v[46:49]
	v_mfma_f32_16x16x32_bf16 v[58:61], v[158:161], v[194:197], v[58:61]
	v_mfma_f32_16x16x32_bf16 v[58:61], v[154:157], v[190:193], v[58:61]
	v_mfma_f32_16x16x32_bf16 v[50:53], v[162:165], v[190:193], v[50:53]
	v_mfma_f32_16x16x32_bf16 v[50:53], v[166:169], v[194:197], v[50:53]
	v_mfma_f32_16x16x32_bf16 v[34:37], v[166:169], v[202:205], v[34:37]
	v_mfma_f32_16x16x32_bf16 v[34:37], v[162:165], v[198:201], v[34:37]
	v_mfma_f32_16x16x32_bf16 v[18:21], v[162:165], v[206:209], v[18:21]
	v_mfma_f32_16x16x32_bf16 v[18:21], v[166:169], v[228:231], v[18:21]
	v_mfma_f32_16x16x32_bf16 v[6:9], v[166:169], v[236:239], v[6:9]
	v_mfma_f32_16x16x32_bf16 v[6:9], v[162:165], v[232:235], v[6:9]
	v_mfma_f32_16x16x32_bf16 v[2:5], v[170:173], v[232:235], v[2:5]
	v_mfma_f32_16x16x32_bf16 v[2:5], v[178:181], v[236:239], v[2:5]
	v_mfma_f32_16x16x32_bf16 v[10:13], v[178:181], v[228:231], v[10:13]
	v_mfma_f32_16x16x32_bf16 v[10:13], v[170:173], v[206:209], v[10:13]
	v_mfma_f32_16x16x32_bf16 v[26:29], v[170:173], v[198:201], v[26:29]
	v_mfma_f32_16x16x32_bf16 v[26:29], v[178:181], v[202:205], v[26:29]
	v_mfma_f32_16x16x32_bf16 v[42:45], v[178:181], v[194:197], v[42:45]
	v_mfma_f32_16x16x32_bf16 v[42:45], v[170:173], v[190:193], v[42:45]
	s_barrier
	s_setprio 0
	s_add_i32 s48, s48, 2
	s_add_u32 s46, s46, 0x100
	s_addc_u32 s47, s47, 0
	s_cmpk_gt_u32 s48, 0xa9
	s_mov_b64 s[14:15], s[16:17]
	s_cbranch_scc0 .LBB0_805
	s_and_b64 vcc, exec, s[6:7]
	s_cbranch_vccz .LBB0_808
	s_barrier
